# phase-5 GEMM epilogue rewritten as four straight-line per-kind blocks (o, zm, g_m, g_p): packed f32 mul/add, all tile read-backs in flight behind the activations, counted vmcnt
# speedup vs baseline: 1.0768x; 1.0209x over previous
;     __device__ __forceinline__ void operator()(const f32x4 (&acc)[2][2][4][2], const Unit& u, int wr, int wc, int fr, int fq) const {
;         const int wt = u.pn - 72;
;         const int gl_off = ((wr * 4 + wc) * 16 * 64 + (fq * 16 + fr)) * 8;
;         const int row0 = u.pm * 256 + wr * 64 + fr, col0 = wc * 32 + 8 * fq;
;         const bf16_t* ldp = nullptr; bf16_t* stp; bool ld_lm = false, st_lm = false, act_silu = false, recip = false; int ld = 0;
;         if (wt < 16) { bf16_t* t = (bf16_t*)(ws + OFF_Q) + (size_t)(u.pm * 4 + (wt - 12)) * 65536 + gl_off; ldp = t; stp = t; ld_lm = st_lm = true; }
;         else if (wt < 20) { ldp = (const bf16_t*)(ws + OFF_Q) + (size_t)(u.pm * 4 + (wt - 16)) * 65536 + gl_off; ld_lm = true; stp = am + (wt - 16) * 256; ld = 1024; act_silu = true; }
;         else if (wt < 24) { bf16_t* t = (bf16_t*)(ws + OFF_PM) + (wt - 22) * 256; ldp = t; stp = t; ld = 512; act_silu = true; }
;         else if (wt < 28) { stp = (bf16_t*)(ws + OFF_GB) + (size_t)(u.pm * 8 + (wt - 24)) * 65536 + gl_off; st_lm = true; }
;         else { bf16_t* t = (bf16_t*)(ws + OFF_GB) + (size_t)(u.pm * 8 + (wt - 24)) * 65536 + gl_off; stp = t; st_lm = true; ldp = t - 4 * 65536; ld_lm = true; recip = true; }
;     ...
;                 for (int bj = 0; bj < 2; ++bj) { const f32x4 a0 = acc[ai][bj][m][0], a1 = acc[ai][bj][m][1];
;                     float f[8];
; #pragma unroll
;                     for (int q = 0; q < 4; ++q) { f[q] = act_silu ? siluf(a0[q]) : sigm(a0[q]); f[4 + q] = act_silu ? siluf(a1[q]) : sigm(a1[q]); }
;                     if (ldp) { const u32x4 o = old8[m][bj];
;                         if (recip) { f[0] *= __builtin_amdgcn_rcpf(bf_lo(o.x)); f[1] *= __builtin_amdgcn_rcpf(bf_hi(o.x)); f[2] *= __builtin_amdgcn_rcpf(bf_lo(o.y)); f[3] *= __builtin_amdgcn_rcpf(bf_hi(o.y));
;                             f[4] *= __builtin_amdgcn_rcpf(bf_lo(o.z)); f[5] *= __builtin_amdgcn_rcpf(bf_hi(o.z)); f[6] *= __builtin_amdgcn_rcpf(bf_lo(o.w)); f[7] *= __builtin_amdgcn_rcpf(bf_hi(o.w)); }
;                         else { f[0] *= bf_lo(o.x); f[1] *= bf_hi(o.x); f[2] *= bf_lo(o.y); f[3] *= bf_hi(o.y); f[4] *= bf_lo(o.z); f[5] *= bf_hi(o.z); f[6] *= bf_lo(o.w); f[7] *= bf_hi(o.w); } }
;                     u32x4 w; w.x = cvt_pk_bf16(f[0], f[1]); w.y = cvt_pk_bf16(f[2], f[3]); w.z = cvt_pk_bf16(f[4], f[5]); w.w = cvt_pk_bf16(f[6], f[7]);
.Lgb4_skip:
	s_mov_b32 s4, 0xbfb8aa3b
	s_mov_b32 s5, s4
	s_mov_b32 s6, 1.0
	s_mov_b32 s7, 1.0
	s_mov_b64 s[2:3], 0x1000
	s_mov_b32 s1, 0xffff0000
	s_cmpk_lt_i32 s38, 0x58
	s_cbranch_scc1 .Lep5_o
	s_cmpk_lt_i32 s38, 0x60
	s_cbranch_scc1 .Lep5_zm
	s_cmpk_lt_i32 s38, 0x64
	s_cbranch_scc1 .Lep5_gm
	s_add_i32 s60, s87, s38
	s_ashr_i32 s61, s60, 31
	s_lshl_b64 s[60:61], s[60:61], 17
	s_sub_u32 s60, s60, 0x80000
	s_subb_u32 s61, s61, 0
	v_lshl_add_u64 v[196:197], v[174:175], 0, s[60:61]
	v_lshl_add_u64 v[198:199], v[196:197], 0, s[2:3]
	v_lshl_add_u64 v[200:201], v[198:199], 0, s[2:3]
	v_lshl_add_u64 v[202:203], v[200:201], 0, s[2:3]
	global_load_dwordx4 v[116:119], v[196:197], off
	global_load_dwordx4 v[104:107], v[196:197], off offset:1024
	global_load_dwordx4 v[92:95], v[196:197], off offset:2048
	global_load_dwordx4 v[80:83], v[196:197], off offset:3072
	global_load_dwordx4 v[76:79], v[198:199], off
	global_load_dwordx4 v[64:67], v[198:199], off offset:1024
	global_load_dwordx4 v[52:55], v[198:199], off offset:2048
	global_load_dwordx4 v[40:43], v[198:199], off offset:3072
	global_load_dwordx4 v[228:231], v[200:201], off
	global_load_dwordx4 v[232:235], v[200:201], off offset:1024
	global_load_dwordx4 v[236:239], v[200:201], off offset:2048
	global_load_dwordx4 v[240:243], v[200:201], off offset:3072
	global_load_dwordx4 v[244:247], v[202:203], off
	global_load_dwordx4 v[248:251], v[202:203], off offset:1024
	global_load_dwordx4 v[206:209], v[202:203], off offset:2048
	global_load_dwordx4 v[210:213], v[202:203], off offset:3072
	v_pk_mul_f32 v[214:215], v[152:153], s[4:5]
	v_pk_mul_f32 v[216:217], v[154:155], s[4:5]
	v_pk_mul_f32 v[218:219], v[156:157], s[4:5]
	v_pk_mul_f32 v[220:221], v[158:159], s[4:5]
	v_exp_f32_e32 v214, v214
	v_exp_f32_e32 v215, v215
	v_exp_f32_e32 v216, v216
	v_exp_f32_e32 v217, v217
	v_exp_f32_e32 v218, v218
	v_exp_f32_e32 v219, v219
	v_exp_f32_e32 v220, v220
	v_exp_f32_e32 v221, v221
	v_pk_add_f32 v[214:215], v[214:215], s[6:7]
	v_pk_add_f32 v[216:217], v[216:217], s[6:7]
	v_pk_add_f32 v[218:219], v[218:219], s[6:7]
	v_pk_add_f32 v[220:221], v[220:221], s[6:7]
	v_rcp_f32_e32 v152, v214
	v_rcp_f32_e32 v153, v215
	v_rcp_f32_e32 v154, v216
	v_rcp_f32_e32 v155, v217
	v_rcp_f32_e32 v156, v218
	v_rcp_f32_e32 v157, v219
	v_rcp_f32_e32 v158, v220
	v_rcp_f32_e32 v159, v221
	v_pk_mul_f32 v[214:215], v[144:145], s[4:5]
	v_pk_mul_f32 v[216:217], v[146:147], s[4:5]
	v_pk_mul_f32 v[218:219], v[148:149], s[4:5]
	v_pk_mul_f32 v[220:221], v[150:151], s[4:5]
	v_exp_f32_e32 v214, v214
	v_exp_f32_e32 v215, v215
	v_exp_f32_e32 v216, v216
	v_exp_f32_e32 v217, v217
	v_exp_f32_e32 v218, v218
	v_exp_f32_e32 v219, v219
	v_exp_f32_e32 v220, v220
	v_exp_f32_e32 v221, v221
	v_pk_add_f32 v[214:215], v[214:215], s[6:7]
	v_pk_add_f32 v[216:217], v[216:217], s[6:7]
	v_pk_add_f32 v[218:219], v[218:219], s[6:7]
	v_pk_add_f32 v[220:221], v[220:221], s[6:7]
	v_rcp_f32_e32 v144, v214
	v_rcp_f32_e32 v145, v215
	v_rcp_f32_e32 v146, v216
	v_rcp_f32_e32 v147, v217
	v_rcp_f32_e32 v148, v218
	v_rcp_f32_e32 v149, v219
	v_rcp_f32_e32 v150, v220
	v_rcp_f32_e32 v151, v221
	v_pk_mul_f32 v[214:215], v[136:137], s[4:5]
	v_pk_mul_f32 v[216:217], v[138:139], s[4:5]
	v_pk_mul_f32 v[218:219], v[140:141], s[4:5]
	v_pk_mul_f32 v[220:221], v[142:143], s[4:5]
	v_exp_f32_e32 v214, v214
	v_exp_f32_e32 v215, v215
	v_exp_f32_e32 v216, v216
	v_exp_f32_e32 v217, v217
	v_exp_f32_e32 v218, v218
	v_exp_f32_e32 v219, v219
	v_exp_f32_e32 v220, v220
	v_exp_f32_e32 v221, v221
	v_pk_add_f32 v[214:215], v[214:215], s[6:7]
	v_pk_add_f32 v[216:217], v[216:217], s[6:7]
	v_pk_add_f32 v[218:219], v[218:219], s[6:7]
	v_pk_add_f32 v[220:221], v[220:221], s[6:7]
	v_rcp_f32_e32 v136, v214
	v_rcp_f32_e32 v137, v215
	v_rcp_f32_e32 v138, v216
	v_rcp_f32_e32 v139, v217
	v_rcp_f32_e32 v140, v218
	v_rcp_f32_e32 v141, v219
	v_rcp_f32_e32 v142, v220
	v_rcp_f32_e32 v143, v221
	v_pk_mul_f32 v[214:215], v[128:129], s[4:5]
	v_pk_mul_f32 v[216:217], v[130:131], s[4:5]
	v_pk_mul_f32 v[218:219], v[132:133], s[4:5]
	v_pk_mul_f32 v[220:221], v[134:135], s[4:5]
	v_exp_f32_e32 v214, v214
	v_exp_f32_e32 v215, v215
	v_exp_f32_e32 v216, v216
	v_exp_f32_e32 v217, v217
	v_exp_f32_e32 v218, v218
	v_exp_f32_e32 v219, v219
	v_exp_f32_e32 v220, v220
	v_exp_f32_e32 v221, v221
	v_pk_add_f32 v[214:215], v[214:215], s[6:7]
	v_pk_add_f32 v[216:217], v[216:217], s[6:7]
	v_pk_add_f32 v[218:219], v[218:219], s[6:7]
	v_pk_add_f32 v[220:221], v[220:221], s[6:7]
	v_rcp_f32_e32 v128, v214
	v_rcp_f32_e32 v129, v215
	v_rcp_f32_e32 v130, v216
	v_rcp_f32_e32 v131, v217
	v_rcp_f32_e32 v132, v218
	v_rcp_f32_e32 v133, v219
	v_rcp_f32_e32 v134, v220
	v_rcp_f32_e32 v135, v221
	v_pk_mul_f32 v[214:215], v[120:121], s[4:5]
	v_pk_mul_f32 v[216:217], v[122:123], s[4:5]
	v_pk_mul_f32 v[218:219], v[124:125], s[4:5]
	v_pk_mul_f32 v[220:221], v[126:127], s[4:5]
	v_exp_f32_e32 v214, v214
	v_exp_f32_e32 v215, v215
	v_exp_f32_e32 v216, v216
	v_exp_f32_e32 v217, v217
	v_exp_f32_e32 v218, v218
	v_exp_f32_e32 v219, v219
	v_exp_f32_e32 v220, v220
	v_exp_f32_e32 v221, v221
	v_pk_add_f32 v[214:215], v[214:215], s[6:7]
	v_pk_add_f32 v[216:217], v[216:217], s[6:7]
	v_pk_add_f32 v[218:219], v[218:219], s[6:7]
	v_pk_add_f32 v[220:221], v[220:221], s[6:7]
	v_rcp_f32_e32 v120, v214
	v_rcp_f32_e32 v121, v215
	v_rcp_f32_e32 v122, v216
	v_rcp_f32_e32 v123, v217
	v_rcp_f32_e32 v124, v218
	v_rcp_f32_e32 v125, v219
	v_rcp_f32_e32 v126, v220
	v_rcp_f32_e32 v127, v221
	v_pk_mul_f32 v[214:215], v[108:109], s[4:5]
	v_pk_mul_f32 v[216:217], v[110:111], s[4:5]
	v_pk_mul_f32 v[218:219], v[112:113], s[4:5]
	v_pk_mul_f32 v[220:221], v[114:115], s[4:5]
	v_exp_f32_e32 v214, v214
; __device__ __forceinline__ float sigm(float x) { return __builtin_amdgcn_rcpf(1.0f + __expf(-x)); }
; __device__ __forceinline__ float siluf(float x) { return x * __builtin_amdgcn_rcpf(1.0f + __expf(-x)); }
;     __device__ __forceinline__ void operator()(const f32x4 (&acc)[2][2][4][2], const Unit& u, int wr, int wc, int fr, int fq) const {
;     ...
;                 for (int bj = 0; bj < 2; ++bj) { const f32x4 a0 = acc[ai][bj][m][0], a1 = acc[ai][bj][m][1];
;                     float f[8];
; #pragma unroll
;                     for (int q = 0; q < 4; ++q) { f[q] = act_silu ? siluf(a0[q]) : sigm(a0[q]); f[4 + q] = act_silu ? siluf(a1[q]) : sigm(a1[q]); }
	v_exp_f32_e32 v215, v215
	v_exp_f32_e32 v216, v216
	v_exp_f32_e32 v217, v217
	v_exp_f32_e32 v218, v218
	v_exp_f32_e32 v219, v219
	v_exp_f32_e32 v220, v220
	v_exp_f32_e32 v221, v221
	v_pk_add_f32 v[214:215], v[214:215], s[6:7]
	v_pk_add_f32 v[216:217], v[216:217], s[6:7]
	v_pk_add_f32 v[218:219], v[218:219], s[6:7]
	v_pk_add_f32 v[220:221], v[220:221], s[6:7]
	v_rcp_f32_e32 v108, v214
	v_rcp_f32_e32 v109, v215
	v_rcp_f32_e32 v110, v216
	v_rcp_f32_e32 v111, v217
	v_rcp_f32_e32 v112, v218
	v_rcp_f32_e32 v113, v219
	v_rcp_f32_e32 v114, v220
	v_rcp_f32_e32 v115, v221
	v_pk_mul_f32 v[214:215], v[96:97], s[4:5]
	v_pk_mul_f32 v[216:217], v[98:99], s[4:5]
	v_pk_mul_f32 v[218:219], v[100:101], s[4:5]
	v_pk_mul_f32 v[220:221], v[102:103], s[4:5]
	v_exp_f32_e32 v214, v214
	v_exp_f32_e32 v215, v215
	v_exp_f32_e32 v216, v216
	v_exp_f32_e32 v217, v217
	v_exp_f32_e32 v218, v218
	v_exp_f32_e32 v219, v219
	v_exp_f32_e32 v220, v220
	v_exp_f32_e32 v221, v221
	v_pk_add_f32 v[214:215], v[214:215], s[6:7]
	v_pk_add_f32 v[216:217], v[216:217], s[6:7]
	v_pk_add_f32 v[218:219], v[218:219], s[6:7]
	v_pk_add_f32 v[220:221], v[220:221], s[6:7]
	v_rcp_f32_e32 v96, v214
	v_rcp_f32_e32 v97, v215
	v_rcp_f32_e32 v98, v216
	v_rcp_f32_e32 v99, v217
	v_rcp_f32_e32 v100, v218
	v_rcp_f32_e32 v101, v219
	v_rcp_f32_e32 v102, v220
	v_rcp_f32_e32 v103, v221
	v_pk_mul_f32 v[214:215], v[84:85], s[4:5]
	v_pk_mul_f32 v[216:217], v[86:87], s[4:5]
	v_pk_mul_f32 v[218:219], v[88:89], s[4:5]
	v_pk_mul_f32 v[220:221], v[90:91], s[4:5]
	v_exp_f32_e32 v214, v214
	v_exp_f32_e32 v215, v215
	v_exp_f32_e32 v216, v216
	v_exp_f32_e32 v217, v217
	v_exp_f32_e32 v218, v218
	v_exp_f32_e32 v219, v219
	v_exp_f32_e32 v220, v220
	v_exp_f32_e32 v221, v221
	v_pk_add_f32 v[214:215], v[214:215], s[6:7]
	v_pk_add_f32 v[216:217], v[216:217], s[6:7]
	v_pk_add_f32 v[218:219], v[218:219], s[6:7]
	v_pk_add_f32 v[220:221], v[220:221], s[6:7]
	v_rcp_f32_e32 v84, v214
	v_rcp_f32_e32 v85, v215
	v_rcp_f32_e32 v86, v216
	v_rcp_f32_e32 v87, v217
	v_rcp_f32_e32 v88, v218
	v_rcp_f32_e32 v89, v219
	v_rcp_f32_e32 v90, v220
	v_rcp_f32_e32 v91, v221
	v_pk_mul_f32 v[214:215], v[68:69], s[4:5]
	v_pk_mul_f32 v[216:217], v[70:71], s[4:5]
	v_pk_mul_f32 v[218:219], v[72:73], s[4:5]
	v_pk_mul_f32 v[220:221], v[74:75], s[4:5]
	v_exp_f32_e32 v214, v214
	v_exp_f32_e32 v215, v215
	v_exp_f32_e32 v216, v216
	v_exp_f32_e32 v217, v217
	v_exp_f32_e32 v218, v218
	v_exp_f32_e32 v219, v219
	v_exp_f32_e32 v220, v220
	v_exp_f32_e32 v221, v221
	v_pk_add_f32 v[214:215], v[214:215], s[6:7]
	v_pk_add_f32 v[216:217], v[216:217], s[6:7]
	v_pk_add_f32 v[218:219], v[218:219], s[6:7]
	v_pk_add_f32 v[220:221], v[220:221], s[6:7]
	v_rcp_f32_e32 v68, v214
	v_rcp_f32_e32 v69, v215
	v_rcp_f32_e32 v70, v216
	v_rcp_f32_e32 v71, v217
	v_rcp_f32_e32 v72, v218
	v_rcp_f32_e32 v73, v219
	v_rcp_f32_e32 v74, v220
	v_rcp_f32_e32 v75, v221
	v_pk_mul_f32 v[214:215], v[56:57], s[4:5]
	v_pk_mul_f32 v[216:217], v[58:59], s[4:5]
	v_pk_mul_f32 v[218:219], v[60:61], s[4:5]
	v_pk_mul_f32 v[220:221], v[62:63], s[4:5]
	v_exp_f32_e32 v214, v214
	v_exp_f32_e32 v215, v215
	v_exp_f32_e32 v216, v216
	v_exp_f32_e32 v217, v217
	v_exp_f32_e32 v218, v218
	v_exp_f32_e32 v219, v219
	v_exp_f32_e32 v220, v220
	v_exp_f32_e32 v221, v221
	v_pk_add_f32 v[214:215], v[214:215], s[6:7]
	v_pk_add_f32 v[216:217], v[216:217], s[6:7]
	v_pk_add_f32 v[218:219], v[218:219], s[6:7]
	v_pk_add_f32 v[220:221], v[220:221], s[6:7]
	v_rcp_f32_e32 v56, v214
	v_rcp_f32_e32 v57, v215
	v_rcp_f32_e32 v58, v216
	v_rcp_f32_e32 v59, v217
	v_rcp_f32_e32 v60, v218
	v_rcp_f32_e32 v61, v219
	v_rcp_f32_e32 v62, v220
	v_rcp_f32_e32 v63, v221
	v_pk_mul_f32 v[214:215], v[44:45], s[4:5]
	v_pk_mul_f32 v[216:217], v[46:47], s[4:5]
	v_pk_mul_f32 v[218:219], v[48:49], s[4:5]
	v_pk_mul_f32 v[220:221], v[50:51], s[4:5]
	v_exp_f32_e32 v214, v214
	v_exp_f32_e32 v215, v215
	v_exp_f32_e32 v216, v216
	v_exp_f32_e32 v217, v217
	v_exp_f32_e32 v218, v218
	v_exp_f32_e32 v219, v219
	v_exp_f32_e32 v220, v220
	v_exp_f32_e32 v221, v221
	v_pk_add_f32 v[214:215], v[214:215], s[6:7]
	v_pk_add_f32 v[216:217], v[216:217], s[6:7]
	v_pk_add_f32 v[218:219], v[218:219], s[6:7]
	v_pk_add_f32 v[220:221], v[220:221], s[6:7]
	v_rcp_f32_e32 v44, v214
	v_rcp_f32_e32 v45, v215
	v_rcp_f32_e32 v46, v216
	v_rcp_f32_e32 v47, v217
	v_rcp_f32_e32 v48, v218
	v_rcp_f32_e32 v49, v219
	v_rcp_f32_e32 v50, v220
	v_rcp_f32_e32 v51, v221
	v_pk_mul_f32 v[214:215], v[32:33], s[4:5]
	v_pk_mul_f32 v[216:217], v[34:35], s[4:5]
	v_pk_mul_f32 v[218:219], v[36:37], s[4:5]
	v_pk_mul_f32 v[220:221], v[38:39], s[4:5]
	v_exp_f32_e32 v214, v214
	v_exp_f32_e32 v215, v215
	v_exp_f32_e32 v216, v216
	v_exp_f32_e32 v217, v217
	v_exp_f32_e32 v218, v218
	v_exp_f32_e32 v219, v219
	v_exp_f32_e32 v220, v220
	v_exp_f32_e32 v221, v221
	v_pk_add_f32 v[214:215], v[214:215], s[6:7]
	v_pk_add_f32 v[216:217], v[216:217], s[6:7]
	v_pk_add_f32 v[218:219], v[218:219], s[6:7]
	v_pk_add_f32 v[220:221], v[220:221], s[6:7]
	v_rcp_f32_e32 v32, v214
	v_rcp_f32_e32 v33, v215
	v_rcp_f32_e32 v34, v216
	v_rcp_f32_e32 v35, v217
	v_rcp_f32_e32 v36, v218
	v_rcp_f32_e32 v37, v219
	v_rcp_f32_e32 v38, v220
	v_rcp_f32_e32 v39, v221
	v_pk_mul_f32 v[214:215], v[24:25], s[4:5]
	v_pk_mul_f32 v[216:217], v[26:27], s[4:5]
	v_pk_mul_f32 v[218:219], v[28:29], s[4:5]
	v_pk_mul_f32 v[220:221], v[30:31], s[4:5]
	v_exp_f32_e32 v214, v214
	v_exp_f32_e32 v215, v215
	v_exp_f32_e32 v216, v216
	v_exp_f32_e32 v217, v217
	v_exp_f32_e32 v218, v218
	v_exp_f32_e32 v219, v219
	v_exp_f32_e32 v220, v220
	v_exp_f32_e32 v221, v221
	v_pk_add_f32 v[214:215], v[214:215], s[6:7]
	v_pk_add_f32 v[216:217], v[216:217], s[6:7]
	v_pk_add_f32 v[218:219], v[218:219], s[6:7]
; __device__ __forceinline__ float bf_lo(unsigned w) { return __uint_as_float(w << 16); }
; __device__ __forceinline__ float bf_hi(unsigned w) { return __uint_as_float(w & 0xffff0000u); }
; __device__ __forceinline__ unsigned cvt_pk_bf16(float lo, float hi) { unsigned r; asm volatile("v_cvt_pk_bf16_f32 %0, %1, %2" : "=v"(r) : "v"(lo), "v"(hi)); return r; }
; __device__ __forceinline__ float sigm(float x) { return __builtin_amdgcn_rcpf(1.0f + __expf(-x)); }
; __device__ __forceinline__ float siluf(float x) { return x * __builtin_amdgcn_rcpf(1.0f + __expf(-x)); }
;     __device__ __forceinline__ void operator()(const f32x4 (&acc)[2][2][4][2], const Unit& u, int wr, int wc, int fr, int fq) const {
;     ...
;                     for (int q = 0; q < 4; ++q) { f[q] = act_silu ? siluf(a0[q]) : sigm(a0[q]); f[4 + q] = act_silu ? siluf(a1[q]) : sigm(a1[q]); }
;                     if (ldp) { const u32x4 o = old8[m][bj];
;                         if (recip) { f[0] *= __builtin_amdgcn_rcpf(bf_lo(o.x)); f[1] *= __builtin_amdgcn_rcpf(bf_hi(o.x)); f[2] *= __builtin_amdgcn_rcpf(bf_lo(o.y)); f[3] *= __builtin_amdgcn_rcpf(bf_hi(o.y));
;                             f[4] *= __builtin_amdgcn_rcpf(bf_lo(o.z)); f[5] *= __builtin_amdgcn_rcpf(bf_hi(o.z)); f[6] *= __builtin_amdgcn_rcpf(bf_lo(o.w)); f[7] *= __builtin_amdgcn_rcpf(bf_hi(o.w)); }
;                         else { f[0] *= bf_lo(o.x); f[1] *= bf_hi(o.x); f[2] *= bf_lo(o.y); f[3] *= bf_hi(o.y); f[4] *= bf_lo(o.z); f[5] *= bf_hi(o.z); f[6] *= bf_lo(o.w); f[7] *= bf_hi(o.w); } }
;                     u32x4 w; w.x = cvt_pk_bf16(f[0], f[1]); w.y = cvt_pk_bf16(f[2], f[3]); w.z = cvt_pk_bf16(f[4], f[5]); w.w = cvt_pk_bf16(f[6], f[7]);
;                     if (st_lm) { if (recip) __builtin_nontemporal_store(w, (u32x4*)(stp + ((ai * 4 + m) * 2 + bj) * 512)); else *(u32x4*)(stp + ((ai * 4 + m) * 2 + bj) * 512) = w; }
	v_pk_add_f32 v[220:221], v[220:221], s[6:7]
	v_rcp_f32_e32 v24, v214
	v_rcp_f32_e32 v25, v215
	v_rcp_f32_e32 v26, v216
	v_rcp_f32_e32 v27, v217
	v_rcp_f32_e32 v28, v218
	v_rcp_f32_e32 v29, v219
	v_rcp_f32_e32 v30, v220
	v_rcp_f32_e32 v31, v221
	v_pk_mul_f32 v[214:215], v[16:17], s[4:5]
	v_pk_mul_f32 v[216:217], v[18:19], s[4:5]
	v_pk_mul_f32 v[218:219], v[20:21], s[4:5]
	v_pk_mul_f32 v[220:221], v[22:23], s[4:5]
	v_exp_f32_e32 v214, v214
	v_exp_f32_e32 v215, v215
	v_exp_f32_e32 v216, v216
	v_exp_f32_e32 v217, v217
	v_exp_f32_e32 v218, v218
	v_exp_f32_e32 v219, v219
	v_exp_f32_e32 v220, v220
	v_exp_f32_e32 v221, v221
	v_pk_add_f32 v[214:215], v[214:215], s[6:7]
	v_pk_add_f32 v[216:217], v[216:217], s[6:7]
	v_pk_add_f32 v[218:219], v[218:219], s[6:7]
	v_pk_add_f32 v[220:221], v[220:221], s[6:7]
	v_rcp_f32_e32 v16, v214
	v_rcp_f32_e32 v17, v215
	v_rcp_f32_e32 v18, v216
	v_rcp_f32_e32 v19, v217
	v_rcp_f32_e32 v20, v218
	v_rcp_f32_e32 v21, v219
	v_rcp_f32_e32 v22, v220
	v_rcp_f32_e32 v23, v221
	v_pk_mul_f32 v[214:215], v[8:9], s[4:5]
	v_pk_mul_f32 v[216:217], v[10:11], s[4:5]
	v_pk_mul_f32 v[218:219], v[12:13], s[4:5]
	v_pk_mul_f32 v[220:221], v[14:15], s[4:5]
	v_exp_f32_e32 v214, v214
	v_exp_f32_e32 v215, v215
	v_exp_f32_e32 v216, v216
	v_exp_f32_e32 v217, v217
	v_exp_f32_e32 v218, v218
	v_exp_f32_e32 v219, v219
	v_exp_f32_e32 v220, v220
	v_exp_f32_e32 v221, v221
	v_pk_add_f32 v[214:215], v[214:215], s[6:7]
	v_pk_add_f32 v[216:217], v[216:217], s[6:7]
	v_pk_add_f32 v[218:219], v[218:219], s[6:7]
	v_pk_add_f32 v[220:221], v[220:221], s[6:7]
	v_rcp_f32_e32 v8, v214
	v_rcp_f32_e32 v9, v215
	v_rcp_f32_e32 v10, v216
	v_rcp_f32_e32 v11, v217
	v_rcp_f32_e32 v12, v218
	v_rcp_f32_e32 v13, v219
	v_rcp_f32_e32 v14, v220
	v_rcp_f32_e32 v15, v221
	v_pk_mul_f32 v[214:215], v[0:1], s[4:5]
	v_pk_mul_f32 v[216:217], v[2:3], s[4:5]
	v_pk_mul_f32 v[218:219], v[4:5], s[4:5]
	v_pk_mul_f32 v[220:221], v[6:7], s[4:5]
	v_exp_f32_e32 v214, v214
	v_exp_f32_e32 v215, v215
	v_exp_f32_e32 v216, v216
	v_exp_f32_e32 v217, v217
	v_exp_f32_e32 v218, v218
	v_exp_f32_e32 v219, v219
	v_exp_f32_e32 v220, v220
	v_exp_f32_e32 v221, v221
	v_pk_add_f32 v[214:215], v[214:215], s[6:7]
	v_pk_add_f32 v[216:217], v[216:217], s[6:7]
	v_pk_add_f32 v[218:219], v[218:219], s[6:7]
	v_pk_add_f32 v[220:221], v[220:221], s[6:7]
	v_rcp_f32_e32 v0, v214
	v_rcp_f32_e32 v1, v215
	v_rcp_f32_e32 v2, v216
	v_rcp_f32_e32 v3, v217
	v_rcp_f32_e32 v4, v218
	v_rcp_f32_e32 v5, v219
	v_rcp_f32_e32 v6, v220
	v_rcp_f32_e32 v7, v221
	s_mov_b64 s[60:61], 0x80000
	v_lshl_add_u64 v[196:197], v[196:197], 0, s[60:61]
	v_lshl_add_u64 v[198:199], v[198:199], 0, s[60:61]
	v_lshl_add_u64 v[200:201], v[200:201], 0, s[60:61]
	v_lshl_add_u64 v[202:203], v[202:203], 0, s[60:61]
	s_waitcnt vmcnt(15)
	v_lshlrev_b32_e32 v214, 16, v116
	v_and_b32_e32 v215, s1, v116
	v_lshlrev_b32_e32 v216, 16, v117
	v_and_b32_e32 v217, s1, v117
	v_lshlrev_b32_e32 v218, 16, v118
	v_and_b32_e32 v219, s1, v118
	v_lshlrev_b32_e32 v220, 16, v119
	v_and_b32_e32 v221, s1, v119
	v_rcp_f32_e32 v214, v214
	v_rcp_f32_e32 v215, v215
	v_rcp_f32_e32 v216, v216
	v_rcp_f32_e32 v217, v217
	v_rcp_f32_e32 v218, v218
	v_rcp_f32_e32 v219, v219
	v_rcp_f32_e32 v220, v220
	v_rcp_f32_e32 v221, v221
	v_pk_mul_f32 v[156:157], v[156:157], v[214:215]
	v_pk_mul_f32 v[158:159], v[158:159], v[216:217]
	v_pk_mul_f32 v[152:153], v[152:153], v[218:219]
	v_pk_mul_f32 v[154:155], v[154:155], v[220:221]
	v_cvt_pk_bf16_f32 v116, v156, v157
	v_cvt_pk_bf16_f32 v117, v158, v159
	v_cvt_pk_bf16_f32 v118, v152, v153
	v_cvt_pk_bf16_f32 v119, v154, v155
	global_store_dwordx4 v[196:197], v[116:119], off nt
	s_waitcnt vmcnt(15)
	v_lshlrev_b32_e32 v214, 16, v104
	v_and_b32_e32 v215, s1, v104
	v_lshlrev_b32_e32 v216, 16, v105
	v_and_b32_e32 v217, s1, v105
	v_lshlrev_b32_e32 v218, 16, v106
	v_and_b32_e32 v219, s1, v106
	v_lshlrev_b32_e32 v220, 16, v107
	v_and_b32_e32 v221, s1, v107
	v_rcp_f32_e32 v214, v214
	v_rcp_f32_e32 v215, v215
	v_rcp_f32_e32 v216, v216
	v_rcp_f32_e32 v217, v217
	v_rcp_f32_e32 v218, v218
	v_rcp_f32_e32 v219, v219
	v_rcp_f32_e32 v220, v220
	v_rcp_f32_e32 v221, v221
	v_pk_mul_f32 v[148:149], v[148:149], v[214:215]
	v_pk_mul_f32 v[150:151], v[150:151], v[216:217]
	v_pk_mul_f32 v[144:145], v[144:145], v[218:219]
	v_pk_mul_f32 v[146:147], v[146:147], v[220:221]
	v_cvt_pk_bf16_f32 v104, v148, v149
	v_cvt_pk_bf16_f32 v105, v150, v151
	v_cvt_pk_bf16_f32 v106, v144, v145
	v_cvt_pk_bf16_f32 v107, v146, v147
	global_store_dwordx4 v[196:197], v[104:107], off offset:1024 nt
	s_waitcnt vmcnt(15)
	v_lshlrev_b32_e32 v214, 16, v92
	v_and_b32_e32 v215, s1, v92
	v_lshlrev_b32_e32 v216, 16, v93
	v_and_b32_e32 v217, s1, v93
	v_lshlrev_b32_e32 v218, 16, v94
	v_and_b32_e32 v219, s1, v94
	v_lshlrev_b32_e32 v220, 16, v95
	v_and_b32_e32 v221, s1, v95
	v_rcp_f32_e32 v214, v214
	v_rcp_f32_e32 v215, v215
	v_rcp_f32_e32 v216, v216
	v_rcp_f32_e32 v217, v217
	v_rcp_f32_e32 v218, v218
	v_rcp_f32_e32 v219, v219
	v_rcp_f32_e32 v220, v220
	v_rcp_f32_e32 v221, v221
	v_pk_mul_f32 v[140:141], v[140:141], v[214:215]
	v_pk_mul_f32 v[142:143], v[142:143], v[216:217]
	v_pk_mul_f32 v[136:137], v[136:137], v[218:219]
	v_pk_mul_f32 v[138:139], v[138:139], v[220:221]
	v_cvt_pk_bf16_f32 v92, v140, v141
	v_cvt_pk_bf16_f32 v93, v142, v143
	v_cvt_pk_bf16_f32 v94, v136, v137
	v_cvt_pk_bf16_f32 v95, v138, v139
	global_store_dwordx4 v[196:197], v[92:95], off offset:2048 nt
	s_waitcnt vmcnt(15)
; __device__ __forceinline__ float bf_lo(unsigned w) { return __uint_as_float(w << 16); }
; __device__ __forceinline__ float bf_hi(unsigned w) { return __uint_as_float(w & 0xffff0000u); }
; __device__ __forceinline__ unsigned cvt_pk_bf16(float lo, float hi) { unsigned r; asm volatile("v_cvt_pk_bf16_f32 %0, %1, %2" : "=v"(r) : "v"(lo), "v"(hi)); return r; }
;     __device__ __forceinline__ void operator()(const f32x4 (&acc)[2][2][4][2], const Unit& u, int wr, int wc, int fr, int fq) const {
;     ...
;                     if (ldp) { const u32x4 o = old8[m][bj];
;                         if (recip) { f[0] *= __builtin_amdgcn_rcpf(bf_lo(o.x)); f[1] *= __builtin_amdgcn_rcpf(bf_hi(o.x)); f[2] *= __builtin_amdgcn_rcpf(bf_lo(o.y)); f[3] *= __builtin_amdgcn_rcpf(bf_hi(o.y));
;                             f[4] *= __builtin_amdgcn_rcpf(bf_lo(o.z)); f[5] *= __builtin_amdgcn_rcpf(bf_hi(o.z)); f[6] *= __builtin_amdgcn_rcpf(bf_lo(o.w)); f[7] *= __builtin_amdgcn_rcpf(bf_hi(o.w)); }
;                         else { f[0] *= bf_lo(o.x); f[1] *= bf_hi(o.x); f[2] *= bf_lo(o.y); f[3] *= bf_hi(o.y); f[4] *= bf_lo(o.z); f[5] *= bf_hi(o.z); f[6] *= bf_lo(o.w); f[7] *= bf_hi(o.w); } }
;                     u32x4 w; w.x = cvt_pk_bf16(f[0], f[1]); w.y = cvt_pk_bf16(f[2], f[3]); w.z = cvt_pk_bf16(f[4], f[5]); w.w = cvt_pk_bf16(f[6], f[7]);
;                     if (st_lm) { if (recip) __builtin_nontemporal_store(w, (u32x4*)(stp + ((ai * 4 + m) * 2 + bj) * 512)); else *(u32x4*)(stp + ((ai * 4 + m) * 2 + bj) * 512) = w; }
	v_lshlrev_b32_e32 v214, 16, v80
	v_and_b32_e32 v215, s1, v80
	v_lshlrev_b32_e32 v216, 16, v81
	v_and_b32_e32 v217, s1, v81
	v_lshlrev_b32_e32 v218, 16, v82
	v_and_b32_e32 v219, s1, v82
	v_lshlrev_b32_e32 v220, 16, v83
	v_and_b32_e32 v221, s1, v83
	v_rcp_f32_e32 v214, v214
	v_rcp_f32_e32 v215, v215
	v_rcp_f32_e32 v216, v216
	v_rcp_f32_e32 v217, v217
	v_rcp_f32_e32 v218, v218
	v_rcp_f32_e32 v219, v219
	v_rcp_f32_e32 v220, v220
	v_rcp_f32_e32 v221, v221
	v_pk_mul_f32 v[132:133], v[132:133], v[214:215]
	v_pk_mul_f32 v[134:135], v[134:135], v[216:217]
	v_pk_mul_f32 v[128:129], v[128:129], v[218:219]
	v_pk_mul_f32 v[130:131], v[130:131], v[220:221]
	v_cvt_pk_bf16_f32 v80, v132, v133
	v_cvt_pk_bf16_f32 v81, v134, v135
	v_cvt_pk_bf16_f32 v82, v128, v129
	v_cvt_pk_bf16_f32 v83, v130, v131
	global_store_dwordx4 v[196:197], v[80:83], off offset:3072 nt
	s_waitcnt vmcnt(15)
	v_lshlrev_b32_e32 v214, 16, v76
	v_and_b32_e32 v215, s1, v76
	v_lshlrev_b32_e32 v216, 16, v77
	v_and_b32_e32 v217, s1, v77
	v_lshlrev_b32_e32 v218, 16, v78
	v_and_b32_e32 v219, s1, v78
	v_lshlrev_b32_e32 v220, 16, v79
	v_and_b32_e32 v221, s1, v79
	v_rcp_f32_e32 v214, v214
	v_rcp_f32_e32 v215, v215
	v_rcp_f32_e32 v216, v216
	v_rcp_f32_e32 v217, v217
	v_rcp_f32_e32 v218, v218
	v_rcp_f32_e32 v219, v219
	v_rcp_f32_e32 v220, v220
	v_rcp_f32_e32 v221, v221
	v_pk_mul_f32 v[124:125], v[124:125], v[214:215]
	v_pk_mul_f32 v[126:127], v[126:127], v[216:217]
	v_pk_mul_f32 v[120:121], v[120:121], v[218:219]
	v_pk_mul_f32 v[122:123], v[122:123], v[220:221]
	v_cvt_pk_bf16_f32 v76, v124, v125
	v_cvt_pk_bf16_f32 v77, v126, v127
	v_cvt_pk_bf16_f32 v78, v120, v121
	v_cvt_pk_bf16_f32 v79, v122, v123
	global_store_dwordx4 v[198:199], v[76:79], off nt
	s_waitcnt vmcnt(15)
	v_lshlrev_b32_e32 v214, 16, v64
	v_and_b32_e32 v215, s1, v64
	v_lshlrev_b32_e32 v216, 16, v65
	v_and_b32_e32 v217, s1, v65
	v_lshlrev_b32_e32 v218, 16, v66
	v_and_b32_e32 v219, s1, v66
	v_lshlrev_b32_e32 v220, 16, v67
	v_and_b32_e32 v221, s1, v67
	v_rcp_f32_e32 v214, v214
	v_rcp_f32_e32 v215, v215
	v_rcp_f32_e32 v216, v216
	v_rcp_f32_e32 v217, v217
	v_rcp_f32_e32 v218, v218
	v_rcp_f32_e32 v219, v219
	v_rcp_f32_e32 v220, v220
	v_rcp_f32_e32 v221, v221
	v_pk_mul_f32 v[112:113], v[112:113], v[214:215]
	v_pk_mul_f32 v[114:115], v[114:115], v[216:217]
	v_pk_mul_f32 v[108:109], v[108:109], v[218:219]
	v_pk_mul_f32 v[110:111], v[110:111], v[220:221]
	v_cvt_pk_bf16_f32 v64, v112, v113
	v_cvt_pk_bf16_f32 v65, v114, v115
	v_cvt_pk_bf16_f32 v66, v108, v109
	v_cvt_pk_bf16_f32 v67, v110, v111
	global_store_dwordx4 v[198:199], v[64:67], off offset:1024 nt
	s_waitcnt vmcnt(15)
	v_lshlrev_b32_e32 v214, 16, v52
	v_and_b32_e32 v215, s1, v52
	v_lshlrev_b32_e32 v216, 16, v53
	v_and_b32_e32 v217, s1, v53
	v_lshlrev_b32_e32 v218, 16, v54
	v_and_b32_e32 v219, s1, v54
	v_lshlrev_b32_e32 v220, 16, v55
	v_and_b32_e32 v221, s1, v55
	v_rcp_f32_e32 v214, v214
	v_rcp_f32_e32 v215, v215
	v_rcp_f32_e32 v216, v216
	v_rcp_f32_e32 v217, v217
	v_rcp_f32_e32 v218, v218
	v_rcp_f32_e32 v219, v219
	v_rcp_f32_e32 v220, v220
	v_rcp_f32_e32 v221, v221
	v_pk_mul_f32 v[100:101], v[100:101], v[214:215]
	v_pk_mul_f32 v[102:103], v[102:103], v[216:217]
	v_pk_mul_f32 v[96:97], v[96:97], v[218:219]
	v_pk_mul_f32 v[98:99], v[98:99], v[220:221]
	v_cvt_pk_bf16_f32 v52, v100, v101
	v_cvt_pk_bf16_f32 v53, v102, v103
	v_cvt_pk_bf16_f32 v54, v96, v97
	v_cvt_pk_bf16_f32 v55, v98, v99
	global_store_dwordx4 v[198:199], v[52:55], off offset:2048 nt
	s_waitcnt vmcnt(15)
	v_lshlrev_b32_e32 v214, 16, v40
	v_and_b32_e32 v215, s1, v40
	v_lshlrev_b32_e32 v216, 16, v41
	v_and_b32_e32 v217, s1, v41
	v_lshlrev_b32_e32 v218, 16, v42
	v_and_b32_e32 v219, s1, v42
	v_lshlrev_b32_e32 v220, 16, v43
	v_and_b32_e32 v221, s1, v43
	v_rcp_f32_e32 v214, v214
	v_rcp_f32_e32 v215, v215
	v_rcp_f32_e32 v216, v216
	v_rcp_f32_e32 v217, v217
	v_rcp_f32_e32 v218, v218
	v_rcp_f32_e32 v219, v219
	v_rcp_f32_e32 v220, v220
	v_rcp_f32_e32 v221, v221
	v_pk_mul_f32 v[88:89], v[88:89], v[214:215]
	v_pk_mul_f32 v[90:91], v[90:91], v[216:217]
	v_pk_mul_f32 v[84:85], v[84:85], v[218:219]
	v_pk_mul_f32 v[86:87], v[86:87], v[220:221]
	v_cvt_pk_bf16_f32 v40, v88, v89
	v_cvt_pk_bf16_f32 v41, v90, v91
	v_cvt_pk_bf16_f32 v42, v84, v85
	v_cvt_pk_bf16_f32 v43, v86, v87
	global_store_dwordx4 v[198:199], v[40:43], off offset:3072 nt
	s_waitcnt vmcnt(15)
	v_lshlrev_b32_e32 v214, 16, v228
	v_and_b32_e32 v215, s1, v228
	v_lshlrev_b32_e32 v216, 16, v229
	v_and_b32_e32 v217, s1, v229
	v_lshlrev_b32_e32 v218, 16, v230
	v_and_b32_e32 v219, s1, v230
	v_lshlrev_b32_e32 v220, 16, v231
	v_and_b32_e32 v221, s1, v231
	v_rcp_f32_e32 v214, v214
	v_rcp_f32_e32 v215, v215
	v_rcp_f32_e32 v216, v216
	v_rcp_f32_e32 v217, v217
	v_rcp_f32_e32 v218, v218
	v_rcp_f32_e32 v219, v219
	v_rcp_f32_e32 v220, v220
	v_rcp_f32_e32 v221, v221
	v_pk_mul_f32 v[72:73], v[72:73], v[214:215]
	v_pk_mul_f32 v[74:75], v[74:75], v[216:217]
	v_pk_mul_f32 v[68:69], v[68:69], v[218:219]
	v_pk_mul_f32 v[70:71], v[70:71], v[220:221]
	v_cvt_pk_bf16_f32 v228, v72, v73
	v_cvt_pk_bf16_f32 v229, v74, v75
	v_cvt_pk_bf16_f32 v230, v68, v69
	v_cvt_pk_bf16_f32 v231, v70, v71
	global_store_dwordx4 v[200:201], v[228:231], off nt
	s_waitcnt vmcnt(15)
	v_lshlrev_b32_e32 v214, 16, v232
	v_and_b32_e32 v215, s1, v232
	v_lshlrev_b32_e32 v216, 16, v233
	v_and_b32_e32 v217, s1, v233
	v_lshlrev_b32_e32 v218, 16, v234
	v_and_b32_e32 v219, s1, v234
	v_lshlrev_b32_e32 v220, 16, v235
	v_and_b32_e32 v221, s1, v235
	v_rcp_f32_e32 v214, v214
	v_rcp_f32_e32 v215, v215
	v_rcp_f32_e32 v216, v216
	v_rcp_f32_e32 v217, v217
	v_rcp_f32_e32 v218, v218
	v_rcp_f32_e32 v219, v219
	v_rcp_f32_e32 v220, v220
	v_rcp_f32_e32 v221, v221
	v_pk_mul_f32 v[60:61], v[60:61], v[214:215]
	v_pk_mul_f32 v[62:63], v[62:63], v[216:217]
	v_pk_mul_f32 v[56:57], v[56:57], v[218:219]
	v_pk_mul_f32 v[58:59], v[58:59], v[220:221]
	v_cvt_pk_bf16_f32 v232, v60, v61
	v_cvt_pk_bf16_f32 v233, v62, v63
	v_cvt_pk_bf16_f32 v234, v56, v57
	v_cvt_pk_bf16_f32 v235, v58, v59
	global_store_dwordx4 v[200:201], v[232:235], off offset:1024 nt
	s_waitcnt vmcnt(15)
; __device__ __forceinline__ float bf_lo(unsigned w) { return __uint_as_float(w << 16); }
; __device__ __forceinline__ float bf_hi(unsigned w) { return __uint_as_float(w & 0xffff0000u); }
; __device__ __forceinline__ unsigned cvt_pk_bf16(float lo, float hi) { unsigned r; asm volatile("v_cvt_pk_bf16_f32 %0, %1, %2" : "=v"(r) : "v"(lo), "v"(hi)); return r; }
;     __device__ __forceinline__ void operator()(const f32x4 (&acc)[2][2][4][2], const Unit& u, int wr, int wc, int fr, int fq) const {
;     ...
;                     if (ldp) { const u32x4 o = old8[m][bj];
;                         if (recip) { f[0] *= __builtin_amdgcn_rcpf(bf_lo(o.x)); f[1] *= __builtin_amdgcn_rcpf(bf_hi(o.x)); f[2] *= __builtin_amdgcn_rcpf(bf_lo(o.y)); f[3] *= __builtin_amdgcn_rcpf(bf_hi(o.y));
;                             f[4] *= __builtin_amdgcn_rcpf(bf_lo(o.z)); f[5] *= __builtin_amdgcn_rcpf(bf_hi(o.z)); f[6] *= __builtin_amdgcn_rcpf(bf_lo(o.w)); f[7] *= __builtin_amdgcn_rcpf(bf_hi(o.w)); }
;                         else { f[0] *= bf_lo(o.x); f[1] *= bf_hi(o.x); f[2] *= bf_lo(o.y); f[3] *= bf_hi(o.y); f[4] *= bf_lo(o.z); f[5] *= bf_hi(o.z); f[6] *= bf_lo(o.w); f[7] *= bf_hi(o.w); } }
;                     u32x4 w; w.x = cvt_pk_bf16(f[0], f[1]); w.y = cvt_pk_bf16(f[2], f[3]); w.z = cvt_pk_bf16(f[4], f[5]); w.w = cvt_pk_bf16(f[6], f[7]);
;                     if (st_lm) { if (recip) __builtin_nontemporal_store(w, (u32x4*)(stp + ((ai * 4 + m) * 2 + bj) * 512)); else *(u32x4*)(stp + ((ai * 4 + m) * 2 + bj) * 512) = w; }
;                     else *(u32x4*)(stp + (size_t)(row0 + ai * 128 + m * 16) * ld + col0 + bj * 128) = w; } }
	v_lshlrev_b32_e32 v214, 16, v236
	v_and_b32_e32 v215, s1, v236
	v_lshlrev_b32_e32 v216, 16, v237
	v_and_b32_e32 v217, s1, v237
	v_lshlrev_b32_e32 v218, 16, v238
	v_and_b32_e32 v219, s1, v238
	v_lshlrev_b32_e32 v220, 16, v239
	v_and_b32_e32 v221, s1, v239
	v_rcp_f32_e32 v214, v214
	v_rcp_f32_e32 v215, v215
	v_rcp_f32_e32 v216, v216
	v_rcp_f32_e32 v217, v217
	v_rcp_f32_e32 v218, v218
	v_rcp_f32_e32 v219, v219
	v_rcp_f32_e32 v220, v220
	v_rcp_f32_e32 v221, v221
	v_pk_mul_f32 v[48:49], v[48:49], v[214:215]
	v_pk_mul_f32 v[50:51], v[50:51], v[216:217]
	v_pk_mul_f32 v[44:45], v[44:45], v[218:219]
	v_pk_mul_f32 v[46:47], v[46:47], v[220:221]
	v_cvt_pk_bf16_f32 v236, v48, v49
	v_cvt_pk_bf16_f32 v237, v50, v51
	v_cvt_pk_bf16_f32 v238, v44, v45
	v_cvt_pk_bf16_f32 v239, v46, v47
	global_store_dwordx4 v[200:201], v[236:239], off offset:2048 nt
	s_waitcnt vmcnt(15)
	v_lshlrev_b32_e32 v214, 16, v240
	v_and_b32_e32 v215, s1, v240
	v_lshlrev_b32_e32 v216, 16, v241
	v_and_b32_e32 v217, s1, v241
	v_lshlrev_b32_e32 v218, 16, v242
	v_and_b32_e32 v219, s1, v242
	v_lshlrev_b32_e32 v220, 16, v243
	v_and_b32_e32 v221, s1, v243
	v_rcp_f32_e32 v214, v214
	v_rcp_f32_e32 v215, v215
	v_rcp_f32_e32 v216, v216
	v_rcp_f32_e32 v217, v217
	v_rcp_f32_e32 v218, v218
	v_rcp_f32_e32 v219, v219
	v_rcp_f32_e32 v220, v220
	v_rcp_f32_e32 v221, v221
	v_pk_mul_f32 v[36:37], v[36:37], v[214:215]
	v_pk_mul_f32 v[38:39], v[38:39], v[216:217]
	v_pk_mul_f32 v[32:33], v[32:33], v[218:219]
	v_pk_mul_f32 v[34:35], v[34:35], v[220:221]
	v_cvt_pk_bf16_f32 v240, v36, v37
	v_cvt_pk_bf16_f32 v241, v38, v39
	v_cvt_pk_bf16_f32 v242, v32, v33
	v_cvt_pk_bf16_f32 v243, v34, v35
	global_store_dwordx4 v[200:201], v[240:243], off offset:3072 nt
	s_waitcnt vmcnt(15)
	v_lshlrev_b32_e32 v214, 16, v244
	v_and_b32_e32 v215, s1, v244
	v_lshlrev_b32_e32 v216, 16, v245
	v_and_b32_e32 v217, s1, v245
	v_lshlrev_b32_e32 v218, 16, v246
	v_and_b32_e32 v219, s1, v246
	v_lshlrev_b32_e32 v220, 16, v247
	v_and_b32_e32 v221, s1, v247
	v_rcp_f32_e32 v214, v214
	v_rcp_f32_e32 v215, v215
	v_rcp_f32_e32 v216, v216
	v_rcp_f32_e32 v217, v217
	v_rcp_f32_e32 v218, v218
	v_rcp_f32_e32 v219, v219
	v_rcp_f32_e32 v220, v220
	v_rcp_f32_e32 v221, v221
	v_pk_mul_f32 v[28:29], v[28:29], v[214:215]
	v_pk_mul_f32 v[30:31], v[30:31], v[216:217]
	v_pk_mul_f32 v[24:25], v[24:25], v[218:219]
	v_pk_mul_f32 v[26:27], v[26:27], v[220:221]
	v_cvt_pk_bf16_f32 v244, v28, v29
	v_cvt_pk_bf16_f32 v245, v30, v31
	v_cvt_pk_bf16_f32 v246, v24, v25
	v_cvt_pk_bf16_f32 v247, v26, v27
	global_store_dwordx4 v[202:203], v[244:247], off nt
	s_waitcnt vmcnt(15)
	v_lshlrev_b32_e32 v214, 16, v248
	v_and_b32_e32 v215, s1, v248
	v_lshlrev_b32_e32 v216, 16, v249
	v_and_b32_e32 v217, s1, v249
	v_lshlrev_b32_e32 v218, 16, v250
	v_and_b32_e32 v219, s1, v250
	v_lshlrev_b32_e32 v220, 16, v251
	v_and_b32_e32 v221, s1, v251
	v_rcp_f32_e32 v214, v214
	v_rcp_f32_e32 v215, v215
	v_rcp_f32_e32 v216, v216
	v_rcp_f32_e32 v217, v217
	v_rcp_f32_e32 v218, v218
	v_rcp_f32_e32 v219, v219
	v_rcp_f32_e32 v220, v220
	v_rcp_f32_e32 v221, v221
	v_pk_mul_f32 v[20:21], v[20:21], v[214:215]
	v_pk_mul_f32 v[22:23], v[22:23], v[216:217]
	v_pk_mul_f32 v[16:17], v[16:17], v[218:219]
	v_pk_mul_f32 v[18:19], v[18:19], v[220:221]
	v_cvt_pk_bf16_f32 v248, v20, v21
	v_cvt_pk_bf16_f32 v249, v22, v23
	v_cvt_pk_bf16_f32 v250, v16, v17
	v_cvt_pk_bf16_f32 v251, v18, v19
	global_store_dwordx4 v[202:203], v[248:251], off offset:1024 nt
	s_waitcnt vmcnt(15)
	v_lshlrev_b32_e32 v214, 16, v206
	v_and_b32_e32 v215, s1, v206
	v_lshlrev_b32_e32 v216, 16, v207
	v_and_b32_e32 v217, s1, v207
	v_lshlrev_b32_e32 v218, 16, v208
	v_and_b32_e32 v219, s1, v208
	v_lshlrev_b32_e32 v220, 16, v209
	v_and_b32_e32 v221, s1, v209
	v_rcp_f32_e32 v214, v214
	v_rcp_f32_e32 v215, v215
	v_rcp_f32_e32 v216, v216
	v_rcp_f32_e32 v217, v217
	v_rcp_f32_e32 v218, v218
	v_rcp_f32_e32 v219, v219
	v_rcp_f32_e32 v220, v220
	v_rcp_f32_e32 v221, v221
	v_pk_mul_f32 v[12:13], v[12:13], v[214:215]
	v_pk_mul_f32 v[14:15], v[14:15], v[216:217]
	v_pk_mul_f32 v[8:9], v[8:9], v[218:219]
	v_pk_mul_f32 v[10:11], v[10:11], v[220:221]
	v_cvt_pk_bf16_f32 v206, v12, v13
	v_cvt_pk_bf16_f32 v207, v14, v15
	v_cvt_pk_bf16_f32 v208, v8, v9
	v_cvt_pk_bf16_f32 v209, v10, v11
	global_store_dwordx4 v[202:203], v[206:209], off offset:2048 nt
	s_waitcnt vmcnt(15)
	v_lshlrev_b32_e32 v214, 16, v210
	v_and_b32_e32 v215, s1, v210
	v_lshlrev_b32_e32 v216, 16, v211
	v_and_b32_e32 v217, s1, v211
	v_lshlrev_b32_e32 v218, 16, v212
	v_and_b32_e32 v219, s1, v212
	v_lshlrev_b32_e32 v220, 16, v213
	v_and_b32_e32 v221, s1, v213
	v_rcp_f32_e32 v214, v214
	v_rcp_f32_e32 v215, v215
	v_rcp_f32_e32 v216, v216
	v_rcp_f32_e32 v217, v217
	v_rcp_f32_e32 v218, v218
	v_rcp_f32_e32 v219, v219
	v_rcp_f32_e32 v220, v220
	v_rcp_f32_e32 v221, v221
	v_pk_mul_f32 v[4:5], v[4:5], v[214:215]
	v_pk_mul_f32 v[6:7], v[6:7], v[216:217]
	v_pk_mul_f32 v[0:1], v[0:1], v[218:219]
	v_pk_mul_f32 v[2:3], v[2:3], v[220:221]
	v_cvt_pk_bf16_f32 v210, v4, v5
	v_cvt_pk_bf16_f32 v211, v6, v7
	v_cvt_pk_bf16_f32 v212, v0, v1
	v_cvt_pk_bf16_f32 v213, v2, v3
	global_store_dwordx4 v[202:203], v[210:213], off offset:3072 nt
	s_branch .LBB0_727
; __device__ __forceinline__ float bf_lo(unsigned w) { return __uint_as_float(w << 16); }
; __device__ __forceinline__ float bf_hi(unsigned w) { return __uint_as_float(w & 0xffff0000u); }
; __device__ __forceinline__ unsigned cvt_pk_bf16(float lo, float hi) { unsigned r; asm volatile("v_cvt_pk_bf16_f32 %0, %1, %2" : "=v"(r) : "v"(lo), "v"(hi)); return r; }
; __device__ __forceinline__ float sigm(float x) { return __builtin_amdgcn_rcpf(1.0f + __expf(-x)); }
; __device__ __forceinline__ float siluf(float x) { return x * __builtin_amdgcn_rcpf(1.0f + __expf(-x)); }
;     __device__ __forceinline__ void operator()(const f32x4 (&acc)[2][2][4][2], const Unit& u, int wr, int wc, int fr, int fq) const {
;     ...
;         else if (wt < 28) { stp = (bf16_t*)(ws + OFF_GB) + (size_t)(u.pm * 8 + (wt - 24)) * 65536 + gl_off; st_lm = true; }
;     ...
;                 for (int bj = 0; bj < 2; ++bj) { const f32x4 a0 = acc[ai][bj][m][0], a1 = acc[ai][bj][m][1];
;                     float f[8];
; #pragma unroll
;                     for (int q = 0; q < 4; ++q) { f[q] = act_silu ? siluf(a0[q]) : sigm(a0[q]); f[4 + q] = act_silu ? siluf(a1[q]) : sigm(a1[q]); }
;                     if (ldp) { const u32x4 o = old8[m][bj];
;                         if (recip) { f[0] *= __builtin_amdgcn_rcpf(bf_lo(o.x)); f[1] *= __builtin_amdgcn_rcpf(bf_hi(o.x)); f[2] *= __builtin_amdgcn_rcpf(bf_lo(o.y)); f[3] *= __builtin_amdgcn_rcpf(bf_hi(o.y));
;                             f[4] *= __builtin_amdgcn_rcpf(bf_lo(o.z)); f[5] *= __builtin_amdgcn_rcpf(bf_hi(o.z)); f[6] *= __builtin_amdgcn_rcpf(bf_lo(o.w)); f[7] *= __builtin_amdgcn_rcpf(bf_hi(o.w)); }
;                         else { f[0] *= bf_lo(o.x); f[1] *= bf_hi(o.x); f[2] *= bf_lo(o.y); f[3] *= bf_hi(o.y); f[4] *= bf_lo(o.z); f[5] *= bf_hi(o.z); f[6] *= bf_lo(o.w); f[7] *= bf_hi(o.w); } }
;                     u32x4 w; w.x = cvt_pk_bf16(f[0], f[1]); w.y = cvt_pk_bf16(f[2], f[3]); w.z = cvt_pk_bf16(f[4], f[5]); w.w = cvt_pk_bf16(f[6], f[7]);
;                     if (st_lm) { if (recip) __builtin_nontemporal_store(w, (u32x4*)(stp + ((ai * 4 + m) * 2 + bj) * 512)); else *(u32x4*)(stp + ((ai * 4 + m) * 2 + bj) * 512) = w; }
.Lep5_gm:
	s_add_i32 s60, s87, s38
	s_ashr_i32 s61, s60, 31
	s_lshl_b64 s[60:61], s[60:61], 17
	v_lshl_add_u64 v[196:197], v[174:175], 0, s[60:61]
	v_lshl_add_u64 v[198:199], v[196:197], 0, s[2:3]
	v_lshl_add_u64 v[200:201], v[198:199], 0, s[2:3]
	v_lshl_add_u64 v[202:203], v[200:201], 0, s[2:3]
	v_pk_mul_f32 v[214:215], v[152:153], s[4:5]
	v_pk_mul_f32 v[216:217], v[154:155], s[4:5]
	v_pk_mul_f32 v[218:219], v[156:157], s[4:5]
	v_pk_mul_f32 v[220:221], v[158:159], s[4:5]
	v_exp_f32_e32 v214, v214
	v_exp_f32_e32 v215, v215
	v_exp_f32_e32 v216, v216
	v_exp_f32_e32 v217, v217
	v_exp_f32_e32 v218, v218
	v_exp_f32_e32 v219, v219
	v_exp_f32_e32 v220, v220
	v_exp_f32_e32 v221, v221
	v_pk_add_f32 v[214:215], v[214:215], s[6:7]
	v_pk_add_f32 v[216:217], v[216:217], s[6:7]
	v_pk_add_f32 v[218:219], v[218:219], s[6:7]
	v_pk_add_f32 v[220:221], v[220:221], s[6:7]
	v_rcp_f32_e32 v152, v214
	v_rcp_f32_e32 v153, v215
	v_rcp_f32_e32 v154, v216
	v_rcp_f32_e32 v155, v217
	v_rcp_f32_e32 v156, v218
	v_rcp_f32_e32 v157, v219
	v_rcp_f32_e32 v158, v220
	v_rcp_f32_e32 v159, v221
	v_cvt_pk_bf16_f32 v116, v156, v157
	v_cvt_pk_bf16_f32 v117, v158, v159
	v_cvt_pk_bf16_f32 v118, v152, v153
	v_cvt_pk_bf16_f32 v119, v154, v155
	global_store_dwordx4 v[196:197], v[116:119], off
	v_pk_mul_f32 v[214:215], v[144:145], s[4:5]
	v_pk_mul_f32 v[216:217], v[146:147], s[4:5]
	v_pk_mul_f32 v[218:219], v[148:149], s[4:5]
	v_pk_mul_f32 v[220:221], v[150:151], s[4:5]
	v_exp_f32_e32 v214, v214
	v_exp_f32_e32 v215, v215
	v_exp_f32_e32 v216, v216
	v_exp_f32_e32 v217, v217
	v_exp_f32_e32 v218, v218
	v_exp_f32_e32 v219, v219
	v_exp_f32_e32 v220, v220
	v_exp_f32_e32 v221, v221
	v_pk_add_f32 v[214:215], v[214:215], s[6:7]
	v_pk_add_f32 v[216:217], v[216:217], s[6:7]
	v_pk_add_f32 v[218:219], v[218:219], s[6:7]
	v_pk_add_f32 v[220:221], v[220:221], s[6:7]
	v_rcp_f32_e32 v144, v214
	v_rcp_f32_e32 v145, v215
	v_rcp_f32_e32 v146, v216
	v_rcp_f32_e32 v147, v217
	v_rcp_f32_e32 v148, v218
	v_rcp_f32_e32 v149, v219
	v_rcp_f32_e32 v150, v220
	v_rcp_f32_e32 v151, v221
	v_cvt_pk_bf16_f32 v104, v148, v149
	v_cvt_pk_bf16_f32 v105, v150, v151
	v_cvt_pk_bf16_f32 v106, v144, v145
	v_cvt_pk_bf16_f32 v107, v146, v147
	global_store_dwordx4 v[196:197], v[104:107], off offset:1024
	v_pk_mul_f32 v[214:215], v[136:137], s[4:5]
	v_pk_mul_f32 v[216:217], v[138:139], s[4:5]
	v_pk_mul_f32 v[218:219], v[140:141], s[4:5]
	v_pk_mul_f32 v[220:221], v[142:143], s[4:5]
	v_exp_f32_e32 v214, v214
	v_exp_f32_e32 v215, v215
	v_exp_f32_e32 v216, v216
	v_exp_f32_e32 v217, v217
	v_exp_f32_e32 v218, v218
	v_exp_f32_e32 v219, v219
	v_exp_f32_e32 v220, v220
	v_exp_f32_e32 v221, v221
	v_pk_add_f32 v[214:215], v[214:215], s[6:7]
	v_pk_add_f32 v[216:217], v[216:217], s[6:7]
	v_pk_add_f32 v[218:219], v[218:219], s[6:7]
	v_pk_add_f32 v[220:221], v[220:221], s[6:7]
	v_rcp_f32_e32 v136, v214
	v_rcp_f32_e32 v137, v215
	v_rcp_f32_e32 v138, v216
	v_rcp_f32_e32 v139, v217
	v_rcp_f32_e32 v140, v218
	v_rcp_f32_e32 v141, v219
	v_rcp_f32_e32 v142, v220
	v_rcp_f32_e32 v143, v221
	v_cvt_pk_bf16_f32 v92, v140, v141
	v_cvt_pk_bf16_f32 v93, v142, v143
	v_cvt_pk_bf16_f32 v94, v136, v137
	v_cvt_pk_bf16_f32 v95, v138, v139
	global_store_dwordx4 v[196:197], v[92:95], off offset:2048
	v_pk_mul_f32 v[214:215], v[128:129], s[4:5]
	v_pk_mul_f32 v[216:217], v[130:131], s[4:5]
	v_pk_mul_f32 v[218:219], v[132:133], s[4:5]
	v_pk_mul_f32 v[220:221], v[134:135], s[4:5]
	v_exp_f32_e32 v214, v214
	v_exp_f32_e32 v215, v215
	v_exp_f32_e32 v216, v216
	v_exp_f32_e32 v217, v217
	v_exp_f32_e32 v218, v218
	v_exp_f32_e32 v219, v219
	v_exp_f32_e32 v220, v220
	v_exp_f32_e32 v221, v221
	v_pk_add_f32 v[214:215], v[214:215], s[6:7]
	v_pk_add_f32 v[216:217], v[216:217], s[6:7]
	v_pk_add_f32 v[218:219], v[218:219], s[6:7]
	v_pk_add_f32 v[220:221], v[220:221], s[6:7]
	v_rcp_f32_e32 v128, v214
	v_rcp_f32_e32 v129, v215
	v_rcp_f32_e32 v130, v216
	v_rcp_f32_e32 v131, v217
	v_rcp_f32_e32 v132, v218
	v_rcp_f32_e32 v133, v219
	v_rcp_f32_e32 v134, v220
	v_rcp_f32_e32 v135, v221
	v_cvt_pk_bf16_f32 v80, v132, v133
	v_cvt_pk_bf16_f32 v81, v134, v135
	v_cvt_pk_bf16_f32 v82, v128, v129
	v_cvt_pk_bf16_f32 v83, v130, v131
	global_store_dwordx4 v[196:197], v[80:83], off offset:3072
	v_pk_mul_f32 v[214:215], v[120:121], s[4:5]
	v_pk_mul_f32 v[216:217], v[122:123], s[4:5]
	v_pk_mul_f32 v[218:219], v[124:125], s[4:5]
	v_pk_mul_f32 v[220:221], v[126:127], s[4:5]
	v_exp_f32_e32 v214, v214
	v_exp_f32_e32 v215, v215
	v_exp_f32_e32 v216, v216
	v_exp_f32_e32 v217, v217
	v_exp_f32_e32 v218, v218
	v_exp_f32_e32 v219, v219
	v_exp_f32_e32 v220, v220
	v_exp_f32_e32 v221, v221
	v_pk_add_f32 v[214:215], v[214:215], s[6:7]
	v_pk_add_f32 v[216:217], v[216:217], s[6:7]
	v_pk_add_f32 v[218:219], v[218:219], s[6:7]
	v_pk_add_f32 v[220:221], v[220:221], s[6:7]
	v_rcp_f32_e32 v120, v214
	v_rcp_f32_e32 v121, v215
	v_rcp_f32_e32 v122, v216
	v_rcp_f32_e32 v123, v217
	v_rcp_f32_e32 v124, v218
	v_rcp_f32_e32 v125, v219
	v_rcp_f32_e32 v126, v220
	v_rcp_f32_e32 v127, v221
	v_cvt_pk_bf16_f32 v76, v124, v125
	v_cvt_pk_bf16_f32 v77, v126, v127
	v_cvt_pk_bf16_f32 v78, v120, v121
	v_cvt_pk_bf16_f32 v79, v122, v123
	global_store_dwordx4 v[198:199], v[76:79], off
	v_pk_mul_f32 v[214:215], v[108:109], s[4:5]
	v_pk_mul_f32 v[216:217], v[110:111], s[4:5]
	v_pk_mul_f32 v[218:219], v[112:113], s[4:5]
	v_pk_mul_f32 v[220:221], v[114:115], s[4:5]
	v_exp_f32_e32 v214, v214
	v_exp_f32_e32 v215, v215
	v_exp_f32_e32 v216, v216
	v_exp_f32_e32 v217, v217
	v_exp_f32_e32 v218, v218
	v_exp_f32_e32 v219, v219
	v_exp_f32_e32 v220, v220
	v_exp_f32_e32 v221, v221
	v_pk_add_f32 v[214:215], v[214:215], s[6:7]
	v_pk_add_f32 v[216:217], v[216:217], s[6:7]
; __device__ __forceinline__ float bf_lo(unsigned w) { return __uint_as_float(w << 16); }
; __device__ __forceinline__ float bf_hi(unsigned w) { return __uint_as_float(w & 0xffff0000u); }
; __device__ __forceinline__ unsigned cvt_pk_bf16(float lo, float hi) { unsigned r; asm volatile("v_cvt_pk_bf16_f32 %0, %1, %2" : "=v"(r) : "v"(lo), "v"(hi)); return r; }
; __device__ __forceinline__ float sigm(float x) { return __builtin_amdgcn_rcpf(1.0f + __expf(-x)); }
; __device__ __forceinline__ float siluf(float x) { return x * __builtin_amdgcn_rcpf(1.0f + __expf(-x)); }
;     __device__ __forceinline__ void operator()(const f32x4 (&acc)[2][2][4][2], const Unit& u, int wr, int wc, int fr, int fq) const {
;     ...
;                 for (int bj = 0; bj < 2; ++bj) { const f32x4 a0 = acc[ai][bj][m][0], a1 = acc[ai][bj][m][1];
;                     float f[8];
; #pragma unroll
;                     for (int q = 0; q < 4; ++q) { f[q] = act_silu ? siluf(a0[q]) : sigm(a0[q]); f[4 + q] = act_silu ? siluf(a1[q]) : sigm(a1[q]); }
;                     if (ldp) { const u32x4 o = old8[m][bj];
;                         if (recip) { f[0] *= __builtin_amdgcn_rcpf(bf_lo(o.x)); f[1] *= __builtin_amdgcn_rcpf(bf_hi(o.x)); f[2] *= __builtin_amdgcn_rcpf(bf_lo(o.y)); f[3] *= __builtin_amdgcn_rcpf(bf_hi(o.y));
;                             f[4] *= __builtin_amdgcn_rcpf(bf_lo(o.z)); f[5] *= __builtin_amdgcn_rcpf(bf_hi(o.z)); f[6] *= __builtin_amdgcn_rcpf(bf_lo(o.w)); f[7] *= __builtin_amdgcn_rcpf(bf_hi(o.w)); }
;                         else { f[0] *= bf_lo(o.x); f[1] *= bf_hi(o.x); f[2] *= bf_lo(o.y); f[3] *= bf_hi(o.y); f[4] *= bf_lo(o.z); f[5] *= bf_hi(o.z); f[6] *= bf_lo(o.w); f[7] *= bf_hi(o.w); } }
;                     u32x4 w; w.x = cvt_pk_bf16(f[0], f[1]); w.y = cvt_pk_bf16(f[2], f[3]); w.z = cvt_pk_bf16(f[4], f[5]); w.w = cvt_pk_bf16(f[6], f[7]);
;                     if (st_lm) { if (recip) __builtin_nontemporal_store(w, (u32x4*)(stp + ((ai * 4 + m) * 2 + bj) * 512)); else *(u32x4*)(stp + ((ai * 4 + m) * 2 + bj) * 512) = w; }
	v_pk_add_f32 v[218:219], v[218:219], s[6:7]
	v_pk_add_f32 v[220:221], v[220:221], s[6:7]
	v_rcp_f32_e32 v108, v214
	v_rcp_f32_e32 v109, v215
	v_rcp_f32_e32 v110, v216
	v_rcp_f32_e32 v111, v217
	v_rcp_f32_e32 v112, v218
	v_rcp_f32_e32 v113, v219
	v_rcp_f32_e32 v114, v220
	v_rcp_f32_e32 v115, v221
	v_cvt_pk_bf16_f32 v64, v112, v113
	v_cvt_pk_bf16_f32 v65, v114, v115
	v_cvt_pk_bf16_f32 v66, v108, v109
	v_cvt_pk_bf16_f32 v67, v110, v111
	global_store_dwordx4 v[198:199], v[64:67], off offset:1024
	v_pk_mul_f32 v[214:215], v[96:97], s[4:5]
	v_pk_mul_f32 v[216:217], v[98:99], s[4:5]
	v_pk_mul_f32 v[218:219], v[100:101], s[4:5]
	v_pk_mul_f32 v[220:221], v[102:103], s[4:5]
	v_exp_f32_e32 v214, v214
	v_exp_f32_e32 v215, v215
	v_exp_f32_e32 v216, v216
	v_exp_f32_e32 v217, v217
	v_exp_f32_e32 v218, v218
	v_exp_f32_e32 v219, v219
	v_exp_f32_e32 v220, v220
	v_exp_f32_e32 v221, v221
	v_pk_add_f32 v[214:215], v[214:215], s[6:7]
	v_pk_add_f32 v[216:217], v[216:217], s[6:7]
	v_pk_add_f32 v[218:219], v[218:219], s[6:7]
	v_pk_add_f32 v[220:221], v[220:221], s[6:7]
	v_rcp_f32_e32 v96, v214
	v_rcp_f32_e32 v97, v215
	v_rcp_f32_e32 v98, v216
	v_rcp_f32_e32 v99, v217
	v_rcp_f32_e32 v100, v218
	v_rcp_f32_e32 v101, v219
	v_rcp_f32_e32 v102, v220
	v_rcp_f32_e32 v103, v221
	v_cvt_pk_bf16_f32 v52, v100, v101
	v_cvt_pk_bf16_f32 v53, v102, v103
	v_cvt_pk_bf16_f32 v54, v96, v97
	v_cvt_pk_bf16_f32 v55, v98, v99
	global_store_dwordx4 v[198:199], v[52:55], off offset:2048
	v_pk_mul_f32 v[214:215], v[84:85], s[4:5]
	v_pk_mul_f32 v[216:217], v[86:87], s[4:5]
	v_pk_mul_f32 v[218:219], v[88:89], s[4:5]
	v_pk_mul_f32 v[220:221], v[90:91], s[4:5]
	v_exp_f32_e32 v214, v214
	v_exp_f32_e32 v215, v215
	v_exp_f32_e32 v216, v216
	v_exp_f32_e32 v217, v217
	v_exp_f32_e32 v218, v218
	v_exp_f32_e32 v219, v219
	v_exp_f32_e32 v220, v220
	v_exp_f32_e32 v221, v221
	v_pk_add_f32 v[214:215], v[214:215], s[6:7]
	v_pk_add_f32 v[216:217], v[216:217], s[6:7]
	v_pk_add_f32 v[218:219], v[218:219], s[6:7]
	v_pk_add_f32 v[220:221], v[220:221], s[6:7]
	v_rcp_f32_e32 v84, v214
	v_rcp_f32_e32 v85, v215
	v_rcp_f32_e32 v86, v216
	v_rcp_f32_e32 v87, v217
	v_rcp_f32_e32 v88, v218
	v_rcp_f32_e32 v89, v219
	v_rcp_f32_e32 v90, v220
	v_rcp_f32_e32 v91, v221
	v_cvt_pk_bf16_f32 v40, v88, v89
	v_cvt_pk_bf16_f32 v41, v90, v91
	v_cvt_pk_bf16_f32 v42, v84, v85
	v_cvt_pk_bf16_f32 v43, v86, v87
	global_store_dwordx4 v[198:199], v[40:43], off offset:3072
	v_pk_mul_f32 v[214:215], v[68:69], s[4:5]
	v_pk_mul_f32 v[216:217], v[70:71], s[4:5]
	v_pk_mul_f32 v[218:219], v[72:73], s[4:5]
	v_pk_mul_f32 v[220:221], v[74:75], s[4:5]
	v_exp_f32_e32 v214, v214
	v_exp_f32_e32 v215, v215
	v_exp_f32_e32 v216, v216
	v_exp_f32_e32 v217, v217
	v_exp_f32_e32 v218, v218
	v_exp_f32_e32 v219, v219
	v_exp_f32_e32 v220, v220
	v_exp_f32_e32 v221, v221
	v_pk_add_f32 v[214:215], v[214:215], s[6:7]
	v_pk_add_f32 v[216:217], v[216:217], s[6:7]
	v_pk_add_f32 v[218:219], v[218:219], s[6:7]
	v_pk_add_f32 v[220:221], v[220:221], s[6:7]
	v_rcp_f32_e32 v68, v214
	v_rcp_f32_e32 v69, v215
	v_rcp_f32_e32 v70, v216
	v_rcp_f32_e32 v71, v217
	v_rcp_f32_e32 v72, v218
	v_rcp_f32_e32 v73, v219
	v_rcp_f32_e32 v74, v220
	v_rcp_f32_e32 v75, v221
	v_cvt_pk_bf16_f32 v228, v72, v73
	v_cvt_pk_bf16_f32 v229, v74, v75
	v_cvt_pk_bf16_f32 v230, v68, v69
	v_cvt_pk_bf16_f32 v231, v70, v71
	global_store_dwordx4 v[200:201], v[228:231], off
	v_pk_mul_f32 v[214:215], v[56:57], s[4:5]
	v_pk_mul_f32 v[216:217], v[58:59], s[4:5]
	v_pk_mul_f32 v[218:219], v[60:61], s[4:5]
	v_pk_mul_f32 v[220:221], v[62:63], s[4:5]
	v_exp_f32_e32 v214, v214
	v_exp_f32_e32 v215, v215
	v_exp_f32_e32 v216, v216
	v_exp_f32_e32 v217, v217
	v_exp_f32_e32 v218, v218
	v_exp_f32_e32 v219, v219
	v_exp_f32_e32 v220, v220
	v_exp_f32_e32 v221, v221
	v_pk_add_f32 v[214:215], v[214:215], s[6:7]
	v_pk_add_f32 v[216:217], v[216:217], s[6:7]
	v_pk_add_f32 v[218:219], v[218:219], s[6:7]
	v_pk_add_f32 v[220:221], v[220:221], s[6:7]
	v_rcp_f32_e32 v56, v214
	v_rcp_f32_e32 v57, v215
	v_rcp_f32_e32 v58, v216
	v_rcp_f32_e32 v59, v217
	v_rcp_f32_e32 v60, v218
	v_rcp_f32_e32 v61, v219
	v_rcp_f32_e32 v62, v220
	v_rcp_f32_e32 v63, v221
	v_cvt_pk_bf16_f32 v232, v60, v61
	v_cvt_pk_bf16_f32 v233, v62, v63
	v_cvt_pk_bf16_f32 v234, v56, v57
	v_cvt_pk_bf16_f32 v235, v58, v59
	global_store_dwordx4 v[200:201], v[232:235], off offset:1024
	v_pk_mul_f32 v[214:215], v[44:45], s[4:5]
	v_pk_mul_f32 v[216:217], v[46:47], s[4:5]
	v_pk_mul_f32 v[218:219], v[48:49], s[4:5]
	v_pk_mul_f32 v[220:221], v[50:51], s[4:5]
	v_exp_f32_e32 v214, v214
	v_exp_f32_e32 v215, v215
	v_exp_f32_e32 v216, v216
	v_exp_f32_e32 v217, v217
	v_exp_f32_e32 v218, v218
	v_exp_f32_e32 v219, v219
	v_exp_f32_e32 v220, v220
	v_exp_f32_e32 v221, v221
	v_pk_add_f32 v[214:215], v[214:215], s[6:7]
	v_pk_add_f32 v[216:217], v[216:217], s[6:7]
	v_pk_add_f32 v[218:219], v[218:219], s[6:7]
	v_pk_add_f32 v[220:221], v[220:221], s[6:7]
	v_rcp_f32_e32 v44, v214
	v_rcp_f32_e32 v45, v215
	v_rcp_f32_e32 v46, v216
	v_rcp_f32_e32 v47, v217
	v_rcp_f32_e32 v48, v218
	v_rcp_f32_e32 v49, v219
	v_rcp_f32_e32 v50, v220
	v_rcp_f32_e32 v51, v221
	v_cvt_pk_bf16_f32 v236, v48, v49
	v_cvt_pk_bf16_f32 v237, v50, v51
	v_cvt_pk_bf16_f32 v238, v44, v45
	v_cvt_pk_bf16_f32 v239, v46, v47
	global_store_dwordx4 v[200:201], v[236:239], off offset:2048
	v_pk_mul_f32 v[214:215], v[32:33], s[4:5]
	v_pk_mul_f32 v[216:217], v[34:35], s[4:5]
	v_pk_mul_f32 v[218:219], v[36:37], s[4:5]
	v_pk_mul_f32 v[220:221], v[38:39], s[4:5]
	v_exp_f32_e32 v214, v214
	v_exp_f32_e32 v215, v215
	v_exp_f32_e32 v216, v216
	v_exp_f32_e32 v217, v217
	v_exp_f32_e32 v218, v218
	v_exp_f32_e32 v219, v219
	v_exp_f32_e32 v220, v220
; __device__ __forceinline__ float bf_lo(unsigned w) { return __uint_as_float(w << 16); }
; __device__ __forceinline__ float bf_hi(unsigned w) { return __uint_as_float(w & 0xffff0000u); }
; __device__ __forceinline__ unsigned cvt_pk_bf16(float lo, float hi) { unsigned r; asm volatile("v_cvt_pk_bf16_f32 %0, %1, %2" : "=v"(r) : "v"(lo), "v"(hi)); return r; }
; __device__ __forceinline__ float sigm(float x) { return __builtin_amdgcn_rcpf(1.0f + __expf(-x)); }
; __device__ __forceinline__ float siluf(float x) { return x * __builtin_amdgcn_rcpf(1.0f + __expf(-x)); }
;     __device__ __forceinline__ void operator()(const f32x4 (&acc)[2][2][4][2], const Unit& u, int wr, int wc, int fr, int fq) const {
;     ...
;             for (int m = 0; m < 4; ++m)
; #pragma unroll
;                 for (int bj = 0; bj < 2; ++bj) { const f32x4 a0 = acc[ai][bj][m][0], a1 = acc[ai][bj][m][1];
;                     float f[8];
; #pragma unroll
;                     for (int q = 0; q < 4; ++q) { f[q] = act_silu ? siluf(a0[q]) : sigm(a0[q]); f[4 + q] = act_silu ? siluf(a1[q]) : sigm(a1[q]); }
;                     if (ldp) { const u32x4 o = old8[m][bj];
;                         if (recip) { f[0] *= __builtin_amdgcn_rcpf(bf_lo(o.x)); f[1] *= __builtin_amdgcn_rcpf(bf_hi(o.x)); f[2] *= __builtin_amdgcn_rcpf(bf_lo(o.y)); f[3] *= __builtin_amdgcn_rcpf(bf_hi(o.y));
;                             f[4] *= __builtin_amdgcn_rcpf(bf_lo(o.z)); f[5] *= __builtin_amdgcn_rcpf(bf_hi(o.z)); f[6] *= __builtin_amdgcn_rcpf(bf_lo(o.w)); f[7] *= __builtin_amdgcn_rcpf(bf_hi(o.w)); }
;                         else { f[0] *= bf_lo(o.x); f[1] *= bf_hi(o.x); f[2] *= bf_lo(o.y); f[3] *= bf_hi(o.y); f[4] *= bf_lo(o.z); f[5] *= bf_hi(o.z); f[6] *= bf_lo(o.w); f[7] *= bf_hi(o.w); } }
;                     u32x4 w; w.x = cvt_pk_bf16(f[0], f[1]); w.y = cvt_pk_bf16(f[2], f[3]); w.z = cvt_pk_bf16(f[4], f[5]); w.w = cvt_pk_bf16(f[6], f[7]);
;                     if (st_lm) { if (recip) __builtin_nontemporal_store(w, (u32x4*)(stp + ((ai * 4 + m) * 2 + bj) * 512)); else *(u32x4*)(stp + ((ai * 4 + m) * 2 + bj) * 512) = w; }
;                     else *(u32x4*)(stp + (size_t)(row0 + ai * 128 + m * 16) * ld + col0 + bj * 128) = w; } }
	v_exp_f32_e32 v221, v221
	v_pk_add_f32 v[214:215], v[214:215], s[6:7]
	v_pk_add_f32 v[216:217], v[216:217], s[6:7]
	v_pk_add_f32 v[218:219], v[218:219], s[6:7]
	v_pk_add_f32 v[220:221], v[220:221], s[6:7]
	v_rcp_f32_e32 v32, v214
	v_rcp_f32_e32 v33, v215
	v_rcp_f32_e32 v34, v216
	v_rcp_f32_e32 v35, v217
	v_rcp_f32_e32 v36, v218
	v_rcp_f32_e32 v37, v219
	v_rcp_f32_e32 v38, v220
	v_rcp_f32_e32 v39, v221
	v_cvt_pk_bf16_f32 v240, v36, v37
	v_cvt_pk_bf16_f32 v241, v38, v39
	v_cvt_pk_bf16_f32 v242, v32, v33
	v_cvt_pk_bf16_f32 v243, v34, v35
	global_store_dwordx4 v[200:201], v[240:243], off offset:3072
	v_pk_mul_f32 v[214:215], v[24:25], s[4:5]
	v_pk_mul_f32 v[216:217], v[26:27], s[4:5]
	v_pk_mul_f32 v[218:219], v[28:29], s[4:5]
	v_pk_mul_f32 v[220:221], v[30:31], s[4:5]
	v_exp_f32_e32 v214, v214
	v_exp_f32_e32 v215, v215
	v_exp_f32_e32 v216, v216
	v_exp_f32_e32 v217, v217
	v_exp_f32_e32 v218, v218
	v_exp_f32_e32 v219, v219
	v_exp_f32_e32 v220, v220
	v_exp_f32_e32 v221, v221
	v_pk_add_f32 v[214:215], v[214:215], s[6:7]
	v_pk_add_f32 v[216:217], v[216:217], s[6:7]
	v_pk_add_f32 v[218:219], v[218:219], s[6:7]
	v_pk_add_f32 v[220:221], v[220:221], s[6:7]
	v_rcp_f32_e32 v24, v214
	v_rcp_f32_e32 v25, v215
	v_rcp_f32_e32 v26, v216
	v_rcp_f32_e32 v27, v217
	v_rcp_f32_e32 v28, v218
	v_rcp_f32_e32 v29, v219
	v_rcp_f32_e32 v30, v220
	v_rcp_f32_e32 v31, v221
	v_cvt_pk_bf16_f32 v244, v28, v29
	v_cvt_pk_bf16_f32 v245, v30, v31
	v_cvt_pk_bf16_f32 v246, v24, v25
	v_cvt_pk_bf16_f32 v247, v26, v27
	global_store_dwordx4 v[202:203], v[244:247], off
	v_pk_mul_f32 v[214:215], v[16:17], s[4:5]
	v_pk_mul_f32 v[216:217], v[18:19], s[4:5]
	v_pk_mul_f32 v[218:219], v[20:21], s[4:5]
	v_pk_mul_f32 v[220:221], v[22:23], s[4:5]
	v_exp_f32_e32 v214, v214
	v_exp_f32_e32 v215, v215
	v_exp_f32_e32 v216, v216
	v_exp_f32_e32 v217, v217
	v_exp_f32_e32 v218, v218
	v_exp_f32_e32 v219, v219
	v_exp_f32_e32 v220, v220
	v_exp_f32_e32 v221, v221
	v_pk_add_f32 v[214:215], v[214:215], s[6:7]
	v_pk_add_f32 v[216:217], v[216:217], s[6:7]
	v_pk_add_f32 v[218:219], v[218:219], s[6:7]
	v_pk_add_f32 v[220:221], v[220:221], s[6:7]
	v_rcp_f32_e32 v16, v214
	v_rcp_f32_e32 v17, v215
	v_rcp_f32_e32 v18, v216
	v_rcp_f32_e32 v19, v217
	v_rcp_f32_e32 v20, v218
	v_rcp_f32_e32 v21, v219
	v_rcp_f32_e32 v22, v220
	v_rcp_f32_e32 v23, v221
	v_cvt_pk_bf16_f32 v248, v20, v21
	v_cvt_pk_bf16_f32 v249, v22, v23
	v_cvt_pk_bf16_f32 v250, v16, v17
	v_cvt_pk_bf16_f32 v251, v18, v19
	global_store_dwordx4 v[202:203], v[248:251], off offset:1024
	v_pk_mul_f32 v[214:215], v[8:9], s[4:5]
	v_pk_mul_f32 v[216:217], v[10:11], s[4:5]
	v_pk_mul_f32 v[218:219], v[12:13], s[4:5]
	v_pk_mul_f32 v[220:221], v[14:15], s[4:5]
	v_exp_f32_e32 v214, v214
	v_exp_f32_e32 v215, v215
	v_exp_f32_e32 v216, v216
	v_exp_f32_e32 v217, v217
	v_exp_f32_e32 v218, v218
	v_exp_f32_e32 v219, v219
	v_exp_f32_e32 v220, v220
	v_exp_f32_e32 v221, v221
	v_pk_add_f32 v[214:215], v[214:215], s[6:7]
	v_pk_add_f32 v[216:217], v[216:217], s[6:7]
	v_pk_add_f32 v[218:219], v[218:219], s[6:7]
	v_pk_add_f32 v[220:221], v[220:221], s[6:7]
	v_rcp_f32_e32 v8, v214
	v_rcp_f32_e32 v9, v215
	v_rcp_f32_e32 v10, v216
	v_rcp_f32_e32 v11, v217
	v_rcp_f32_e32 v12, v218
	v_rcp_f32_e32 v13, v219
	v_rcp_f32_e32 v14, v220
	v_rcp_f32_e32 v15, v221
	v_cvt_pk_bf16_f32 v206, v12, v13
	v_cvt_pk_bf16_f32 v207, v14, v15
	v_cvt_pk_bf16_f32 v208, v8, v9
	v_cvt_pk_bf16_f32 v209, v10, v11
	global_store_dwordx4 v[202:203], v[206:209], off offset:2048
	v_pk_mul_f32 v[214:215], v[0:1], s[4:5]
	v_pk_mul_f32 v[216:217], v[2:3], s[4:5]
	v_pk_mul_f32 v[218:219], v[4:5], s[4:5]
	v_pk_mul_f32 v[220:221], v[6:7], s[4:5]
	v_exp_f32_e32 v214, v214
	v_exp_f32_e32 v215, v215
	v_exp_f32_e32 v216, v216
	v_exp_f32_e32 v217, v217
	v_exp_f32_e32 v218, v218
	v_exp_f32_e32 v219, v219
	v_exp_f32_e32 v220, v220
	v_exp_f32_e32 v221, v221
	v_pk_add_f32 v[214:215], v[214:215], s[6:7]
	v_pk_add_f32 v[216:217], v[216:217], s[6:7]
	v_pk_add_f32 v[218:219], v[218:219], s[6:7]
	v_pk_add_f32 v[220:221], v[220:221], s[6:7]
	v_rcp_f32_e32 v0, v214
	v_rcp_f32_e32 v1, v215
	v_rcp_f32_e32 v2, v216
	v_rcp_f32_e32 v3, v217
	v_rcp_f32_e32 v4, v218
	v_rcp_f32_e32 v5, v219
	v_rcp_f32_e32 v6, v220
	v_rcp_f32_e32 v7, v221
	v_cvt_pk_bf16_f32 v210, v4, v5
	v_cvt_pk_bf16_f32 v211, v6, v7
	v_cvt_pk_bf16_f32 v212, v0, v1
	v_cvt_pk_bf16_f32 v213, v2, v3
	global_store_dwordx4 v[202:203], v[210:213], off offset:3072
	s_branch .LBB0_727
; __device__ __forceinline__ float sigm(float x) { return __builtin_amdgcn_rcpf(1.0f + __expf(-x)); }
; __device__ __forceinline__ float siluf(float x) { return x * __builtin_amdgcn_rcpf(1.0f + __expf(-x)); }
;     __device__ __forceinline__ void operator()(const f32x4 (&acc)[2][2][4][2], const Unit& u, int wr, int wc, int fr, int fq) const {
;     ...
;         const int gl_off = ((wr * 4 + wc) * 16 * 64 + (fq * 16 + fr)) * 8;
;         const int row0 = u.pm * 256 + wr * 64 + fr, col0 = wc * 32 + 8 * fq;
;         const bf16_t* ldp = nullptr; bf16_t* stp; bool ld_lm = false, st_lm = false, act_silu = false, recip = false; int ld = 0;
;         if (wt < 16) { bf16_t* t = (bf16_t*)(ws + OFF_Q) + (size_t)(u.pm * 4 + (wt - 12)) * 65536 + gl_off; ldp = t; stp = t; ld_lm = st_lm = true; }
;         else if (wt < 20) { ldp = (const bf16_t*)(ws + OFF_Q) + (size_t)(u.pm * 4 + (wt - 16)) * 65536 + gl_off; ld_lm = true; stp = am + (wt - 16) * 256; ld = 1024; act_silu = true; }
;         else if (wt < 24) { bf16_t* t = (bf16_t*)(ws + OFF_PM) + (wt - 22) * 256; ldp = t; stp = t; ld = 512; act_silu = true; }
;         else if (wt < 28) { stp = (bf16_t*)(ws + OFF_GB) + (size_t)(u.pm * 8 + (wt - 24)) * 65536 + gl_off; st_lm = true; }
;         else { bf16_t* t = (bf16_t*)(ws + OFF_GB) + (size_t)(u.pm * 8 + (wt - 24)) * 65536 + gl_off; stp = t; st_lm = true; ldp = t - 4 * 65536; ld_lm = true; recip = true; }
; #pragma unroll
;         for (int ai = 0; ai < 2; ++ai) {
;             u32x4 old8[4][2];
;             if (ldp) {
; #pragma unroll
;                 for (int m = 0; m < 4; ++m)
; #pragma unroll
;                     for (int bj = 0; bj < 2; ++bj) old8[m][bj] = ld_lm ? *(const u32x4*)(ldp + ((ai * 4 + m) * 2 + bj) * 512)
;                                                                        : *(const u32x4*)(ldp + (size_t)(row0 + ai * 128 + m * 16) * ld + col0 + bj * 128);
;             }
; #pragma unroll
;             for (int m = 0; m < 4; ++m)
; #pragma unroll
;                 for (int bj = 0; bj < 2; ++bj) { const f32x4 a0 = acc[ai][bj][m][0], a1 = acc[ai][bj][m][1];
;                     float f[8];
; #pragma unroll
;                     for (int q = 0; q < 4; ++q) { f[q] = act_silu ? siluf(a0[q]) : sigm(a0[q]); f[4 + q] = act_silu ? siluf(a1[q]) : sigm(a1[q]); }
.Lep5_zm:
	s_add_i32 s60, s88, s38
	s_add_i32 s60, s60, 0xffffffa8
	s_ashr_i32 s61, s60, 31
	s_lshl_b64 s[60:61], s[60:61], 17
	v_lshl_add_u64 v[196:197], v[176:177], 0, s[60:61]
	v_lshl_add_u64 v[198:199], v[196:197], 0, s[2:3]
	v_lshl_add_u64 v[200:201], v[198:199], 0, s[2:3]
	v_lshl_add_u64 v[202:203], v[200:201], 0, s[2:3]
	global_load_dwordx4 v[116:119], v[196:197], off
	global_load_dwordx4 v[104:107], v[196:197], off offset:1024
	global_load_dwordx4 v[92:95], v[196:197], off offset:2048
	global_load_dwordx4 v[80:83], v[196:197], off offset:3072
	global_load_dwordx4 v[76:79], v[198:199], off
	global_load_dwordx4 v[64:67], v[198:199], off offset:1024
	global_load_dwordx4 v[52:55], v[198:199], off offset:2048
	global_load_dwordx4 v[40:43], v[198:199], off offset:3072
	global_load_dwordx4 v[228:231], v[200:201], off
	global_load_dwordx4 v[232:235], v[200:201], off offset:1024
	global_load_dwordx4 v[236:239], v[200:201], off offset:2048
	global_load_dwordx4 v[240:243], v[200:201], off offset:3072
	global_load_dwordx4 v[244:247], v[202:203], off
	global_load_dwordx4 v[248:251], v[202:203], off offset:1024
	global_load_dwordx4 v[206:209], v[202:203], off offset:2048
	global_load_dwordx4 v[210:213], v[202:203], off offset:3072
	s_add_i32 s60, s38, 0xffffffa8
	s_lshl_b32 s60, s60, 9
	s_add_u32 s74, s68, s60
	s_addc_u32 s75, s69, 0
	v_lshlrev_b32_e32 v222, 11, v172
	v_lshl_add_u32 v222, v170, 1, v222
	v_pk_mul_f32 v[214:215], v[152:153], s[4:5]
	v_pk_mul_f32 v[216:217], v[154:155], s[4:5]
	v_pk_mul_f32 v[218:219], v[156:157], s[4:5]
	v_pk_mul_f32 v[220:221], v[158:159], s[4:5]
	v_exp_f32_e32 v214, v214
	v_exp_f32_e32 v215, v215
	v_exp_f32_e32 v216, v216
	v_exp_f32_e32 v217, v217
	v_exp_f32_e32 v218, v218
	v_exp_f32_e32 v219, v219
	v_exp_f32_e32 v220, v220
	v_exp_f32_e32 v221, v221
	v_pk_add_f32 v[214:215], v[214:215], s[6:7]
	v_pk_add_f32 v[216:217], v[216:217], s[6:7]
	v_pk_add_f32 v[218:219], v[218:219], s[6:7]
	v_pk_add_f32 v[220:221], v[220:221], s[6:7]
	v_rcp_f32_e32 v214, v214
	v_rcp_f32_e32 v215, v215
	v_rcp_f32_e32 v216, v216
	v_rcp_f32_e32 v217, v217
	v_rcp_f32_e32 v218, v218
	v_rcp_f32_e32 v219, v219
	v_rcp_f32_e32 v220, v220
	v_rcp_f32_e32 v221, v221
	v_pk_mul_f32 v[152:153], v[152:153], v[214:215]
	v_pk_mul_f32 v[154:155], v[154:155], v[216:217]
	v_pk_mul_f32 v[156:157], v[156:157], v[218:219]
	v_pk_mul_f32 v[158:159], v[158:159], v[220:221]
	v_pk_mul_f32 v[214:215], v[144:145], s[4:5]
	v_pk_mul_f32 v[216:217], v[146:147], s[4:5]
	v_pk_mul_f32 v[218:219], v[148:149], s[4:5]
	v_pk_mul_f32 v[220:221], v[150:151], s[4:5]
	v_exp_f32_e32 v214, v214
	v_exp_f32_e32 v215, v215
	v_exp_f32_e32 v216, v216
	v_exp_f32_e32 v217, v217
	v_exp_f32_e32 v218, v218
	v_exp_f32_e32 v219, v219
	v_exp_f32_e32 v220, v220
	v_exp_f32_e32 v221, v221
	v_pk_add_f32 v[214:215], v[214:215], s[6:7]
	v_pk_add_f32 v[216:217], v[216:217], s[6:7]
	v_pk_add_f32 v[218:219], v[218:219], s[6:7]
	v_pk_add_f32 v[220:221], v[220:221], s[6:7]
	v_rcp_f32_e32 v214, v214
	v_rcp_f32_e32 v215, v215
	v_rcp_f32_e32 v216, v216
	v_rcp_f32_e32 v217, v217
	v_rcp_f32_e32 v218, v218
	v_rcp_f32_e32 v219, v219
	v_rcp_f32_e32 v220, v220
	v_rcp_f32_e32 v221, v221
	v_pk_mul_f32 v[144:145], v[144:145], v[214:215]
	v_pk_mul_f32 v[146:147], v[146:147], v[216:217]
	v_pk_mul_f32 v[148:149], v[148:149], v[218:219]
	v_pk_mul_f32 v[150:151], v[150:151], v[220:221]
	v_pk_mul_f32 v[214:215], v[136:137], s[4:5]
	v_pk_mul_f32 v[216:217], v[138:139], s[4:5]
	v_pk_mul_f32 v[218:219], v[140:141], s[4:5]
	v_pk_mul_f32 v[220:221], v[142:143], s[4:5]
	v_exp_f32_e32 v214, v214
	v_exp_f32_e32 v215, v215
	v_exp_f32_e32 v216, v216
	v_exp_f32_e32 v217, v217
	v_exp_f32_e32 v218, v218
	v_exp_f32_e32 v219, v219
	v_exp_f32_e32 v220, v220
	v_exp_f32_e32 v221, v221
	v_pk_add_f32 v[214:215], v[214:215], s[6:7]
	v_pk_add_f32 v[216:217], v[216:217], s[6:7]
	v_pk_add_f32 v[218:219], v[218:219], s[6:7]
	v_pk_add_f32 v[220:221], v[220:221], s[6:7]
	v_rcp_f32_e32 v214, v214
	v_rcp_f32_e32 v215, v215
	v_rcp_f32_e32 v216, v216
	v_rcp_f32_e32 v217, v217
	v_rcp_f32_e32 v218, v218
	v_rcp_f32_e32 v219, v219
	v_rcp_f32_e32 v220, v220
	v_rcp_f32_e32 v221, v221
	v_pk_mul_f32 v[136:137], v[136:137], v[214:215]
	v_pk_mul_f32 v[138:139], v[138:139], v[216:217]
	v_pk_mul_f32 v[140:141], v[140:141], v[218:219]
	v_pk_mul_f32 v[142:143], v[142:143], v[220:221]
	v_pk_mul_f32 v[214:215], v[128:129], s[4:5]
	v_pk_mul_f32 v[216:217], v[130:131], s[4:5]
	v_pk_mul_f32 v[218:219], v[132:133], s[4:5]
	v_pk_mul_f32 v[220:221], v[134:135], s[4:5]
	v_exp_f32_e32 v214, v214
	v_exp_f32_e32 v215, v215
	v_exp_f32_e32 v216, v216
	v_exp_f32_e32 v217, v217
	v_exp_f32_e32 v218, v218
	v_exp_f32_e32 v219, v219
	v_exp_f32_e32 v220, v220
	v_exp_f32_e32 v221, v221
	v_pk_add_f32 v[214:215], v[214:215], s[6:7]
	v_pk_add_f32 v[216:217], v[216:217], s[6:7]
	v_pk_add_f32 v[218:219], v[218:219], s[6:7]
	v_pk_add_f32 v[220:221], v[220:221], s[6:7]
	v_rcp_f32_e32 v214, v214
	v_rcp_f32_e32 v215, v215
	v_rcp_f32_e32 v216, v216
	v_rcp_f32_e32 v217, v217
	v_rcp_f32_e32 v218, v218
	v_rcp_f32_e32 v219, v219
	v_rcp_f32_e32 v220, v220
	v_rcp_f32_e32 v221, v221
	v_pk_mul_f32 v[128:129], v[128:129], v[214:215]
	v_pk_mul_f32 v[130:131], v[130:131], v[216:217]
	v_pk_mul_f32 v[132:133], v[132:133], v[218:219]
	v_pk_mul_f32 v[134:135], v[134:135], v[220:221]
	v_pk_mul_f32 v[214:215], v[120:121], s[4:5]
	v_pk_mul_f32 v[216:217], v[122:123], s[4:5]
	v_pk_mul_f32 v[218:219], v[124:125], s[4:5]
	v_pk_mul_f32 v[220:221], v[126:127], s[4:5]
	v_exp_f32_e32 v214, v214
	v_exp_f32_e32 v215, v215
	v_exp_f32_e32 v216, v216
	v_exp_f32_e32 v217, v217
	v_exp_f32_e32 v218, v218
	v_exp_f32_e32 v219, v219
; __device__ __forceinline__ float sigm(float x) { return __builtin_amdgcn_rcpf(1.0f + __expf(-x)); }
; __device__ __forceinline__ float siluf(float x) { return x * __builtin_amdgcn_rcpf(1.0f + __expf(-x)); }
;     __device__ __forceinline__ void operator()(const f32x4 (&acc)[2][2][4][2], const Unit& u, int wr, int wc, int fr, int fq) const {
;     ...
;                 for (int bj = 0; bj < 2; ++bj) { const f32x4 a0 = acc[ai][bj][m][0], a1 = acc[ai][bj][m][1];
;                     float f[8];
; #pragma unroll
;                     for (int q = 0; q < 4; ++q) { f[q] = act_silu ? siluf(a0[q]) : sigm(a0[q]); f[4 + q] = act_silu ? siluf(a1[q]) : sigm(a1[q]); }
	v_exp_f32_e32 v220, v220
	v_exp_f32_e32 v221, v221
	v_pk_add_f32 v[214:215], v[214:215], s[6:7]
	v_pk_add_f32 v[216:217], v[216:217], s[6:7]
	v_pk_add_f32 v[218:219], v[218:219], s[6:7]
	v_pk_add_f32 v[220:221], v[220:221], s[6:7]
	v_rcp_f32_e32 v214, v214
	v_rcp_f32_e32 v215, v215
	v_rcp_f32_e32 v216, v216
	v_rcp_f32_e32 v217, v217
	v_rcp_f32_e32 v218, v218
	v_rcp_f32_e32 v219, v219
	v_rcp_f32_e32 v220, v220
	v_rcp_f32_e32 v221, v221
	v_pk_mul_f32 v[120:121], v[120:121], v[214:215]
	v_pk_mul_f32 v[122:123], v[122:123], v[216:217]
	v_pk_mul_f32 v[124:125], v[124:125], v[218:219]
	v_pk_mul_f32 v[126:127], v[126:127], v[220:221]
	v_pk_mul_f32 v[214:215], v[108:109], s[4:5]
	v_pk_mul_f32 v[216:217], v[110:111], s[4:5]
	v_pk_mul_f32 v[218:219], v[112:113], s[4:5]
	v_pk_mul_f32 v[220:221], v[114:115], s[4:5]
	v_exp_f32_e32 v214, v214
	v_exp_f32_e32 v215, v215
	v_exp_f32_e32 v216, v216
	v_exp_f32_e32 v217, v217
	v_exp_f32_e32 v218, v218
	v_exp_f32_e32 v219, v219
	v_exp_f32_e32 v220, v220
	v_exp_f32_e32 v221, v221
	v_pk_add_f32 v[214:215], v[214:215], s[6:7]
	v_pk_add_f32 v[216:217], v[216:217], s[6:7]
	v_pk_add_f32 v[218:219], v[218:219], s[6:7]
	v_pk_add_f32 v[220:221], v[220:221], s[6:7]
	v_rcp_f32_e32 v214, v214
	v_rcp_f32_e32 v215, v215
	v_rcp_f32_e32 v216, v216
	v_rcp_f32_e32 v217, v217
	v_rcp_f32_e32 v218, v218
	v_rcp_f32_e32 v219, v219
	v_rcp_f32_e32 v220, v220
	v_rcp_f32_e32 v221, v221
	v_pk_mul_f32 v[108:109], v[108:109], v[214:215]
	v_pk_mul_f32 v[110:111], v[110:111], v[216:217]
	v_pk_mul_f32 v[112:113], v[112:113], v[218:219]
	v_pk_mul_f32 v[114:115], v[114:115], v[220:221]
	v_pk_mul_f32 v[214:215], v[96:97], s[4:5]
	v_pk_mul_f32 v[216:217], v[98:99], s[4:5]
	v_pk_mul_f32 v[218:219], v[100:101], s[4:5]
	v_pk_mul_f32 v[220:221], v[102:103], s[4:5]
	v_exp_f32_e32 v214, v214
	v_exp_f32_e32 v215, v215
	v_exp_f32_e32 v216, v216
	v_exp_f32_e32 v217, v217
	v_exp_f32_e32 v218, v218
	v_exp_f32_e32 v219, v219
	v_exp_f32_e32 v220, v220
	v_exp_f32_e32 v221, v221
	v_pk_add_f32 v[214:215], v[214:215], s[6:7]
	v_pk_add_f32 v[216:217], v[216:217], s[6:7]
	v_pk_add_f32 v[218:219], v[218:219], s[6:7]
	v_pk_add_f32 v[220:221], v[220:221], s[6:7]
	v_rcp_f32_e32 v214, v214
	v_rcp_f32_e32 v215, v215
	v_rcp_f32_e32 v216, v216
	v_rcp_f32_e32 v217, v217
	v_rcp_f32_e32 v218, v218
	v_rcp_f32_e32 v219, v219
	v_rcp_f32_e32 v220, v220
	v_rcp_f32_e32 v221, v221
	v_pk_mul_f32 v[96:97], v[96:97], v[214:215]
	v_pk_mul_f32 v[98:99], v[98:99], v[216:217]
	v_pk_mul_f32 v[100:101], v[100:101], v[218:219]
	v_pk_mul_f32 v[102:103], v[102:103], v[220:221]
	v_pk_mul_f32 v[214:215], v[84:85], s[4:5]
	v_pk_mul_f32 v[216:217], v[86:87], s[4:5]
	v_pk_mul_f32 v[218:219], v[88:89], s[4:5]
	v_pk_mul_f32 v[220:221], v[90:91], s[4:5]
	v_exp_f32_e32 v214, v214
	v_exp_f32_e32 v215, v215
	v_exp_f32_e32 v216, v216
	v_exp_f32_e32 v217, v217
	v_exp_f32_e32 v218, v218
	v_exp_f32_e32 v219, v219
	v_exp_f32_e32 v220, v220
	v_exp_f32_e32 v221, v221
	v_pk_add_f32 v[214:215], v[214:215], s[6:7]
	v_pk_add_f32 v[216:217], v[216:217], s[6:7]
	v_pk_add_f32 v[218:219], v[218:219], s[6:7]
	v_pk_add_f32 v[220:221], v[220:221], s[6:7]
	v_rcp_f32_e32 v214, v214
	v_rcp_f32_e32 v215, v215
	v_rcp_f32_e32 v216, v216
	v_rcp_f32_e32 v217, v217
	v_rcp_f32_e32 v218, v218
	v_rcp_f32_e32 v219, v219
	v_rcp_f32_e32 v220, v220
	v_rcp_f32_e32 v221, v221
	v_pk_mul_f32 v[84:85], v[84:85], v[214:215]
	v_pk_mul_f32 v[86:87], v[86:87], v[216:217]
	v_pk_mul_f32 v[88:89], v[88:89], v[218:219]
	v_pk_mul_f32 v[90:91], v[90:91], v[220:221]
	v_pk_mul_f32 v[214:215], v[68:69], s[4:5]
	v_pk_mul_f32 v[216:217], v[70:71], s[4:5]
	v_pk_mul_f32 v[218:219], v[72:73], s[4:5]
	v_pk_mul_f32 v[220:221], v[74:75], s[4:5]
	v_exp_f32_e32 v214, v214
	v_exp_f32_e32 v215, v215
	v_exp_f32_e32 v216, v216
	v_exp_f32_e32 v217, v217
	v_exp_f32_e32 v218, v218
	v_exp_f32_e32 v219, v219
	v_exp_f32_e32 v220, v220
	v_exp_f32_e32 v221, v221
	v_pk_add_f32 v[214:215], v[214:215], s[6:7]
	v_pk_add_f32 v[216:217], v[216:217], s[6:7]
	v_pk_add_f32 v[218:219], v[218:219], s[6:7]
	v_pk_add_f32 v[220:221], v[220:221], s[6:7]
	v_rcp_f32_e32 v214, v214
	v_rcp_f32_e32 v215, v215
	v_rcp_f32_e32 v216, v216
	v_rcp_f32_e32 v217, v217
	v_rcp_f32_e32 v218, v218
	v_rcp_f32_e32 v219, v219
	v_rcp_f32_e32 v220, v220
	v_rcp_f32_e32 v221, v221
	v_pk_mul_f32 v[68:69], v[68:69], v[214:215]
	v_pk_mul_f32 v[70:71], v[70:71], v[216:217]
	v_pk_mul_f32 v[72:73], v[72:73], v[218:219]
	v_pk_mul_f32 v[74:75], v[74:75], v[220:221]
	v_pk_mul_f32 v[214:215], v[56:57], s[4:5]
	v_pk_mul_f32 v[216:217], v[58:59], s[4:5]
	v_pk_mul_f32 v[218:219], v[60:61], s[4:5]
	v_pk_mul_f32 v[220:221], v[62:63], s[4:5]
	v_exp_f32_e32 v214, v214
	v_exp_f32_e32 v215, v215
	v_exp_f32_e32 v216, v216
	v_exp_f32_e32 v217, v217
	v_exp_f32_e32 v218, v218
	v_exp_f32_e32 v219, v219
	v_exp_f32_e32 v220, v220
	v_exp_f32_e32 v221, v221
	v_pk_add_f32 v[214:215], v[214:215], s[6:7]
	v_pk_add_f32 v[216:217], v[216:217], s[6:7]
	v_pk_add_f32 v[218:219], v[218:219], s[6:7]
	v_pk_add_f32 v[220:221], v[220:221], s[6:7]
	v_rcp_f32_e32 v214, v214
	v_rcp_f32_e32 v215, v215
	v_rcp_f32_e32 v216, v216
	v_rcp_f32_e32 v217, v217
	v_rcp_f32_e32 v218, v218
	v_rcp_f32_e32 v219, v219
	v_rcp_f32_e32 v220, v220
	v_rcp_f32_e32 v221, v221
	v_pk_mul_f32 v[56:57], v[56:57], v[214:215]
	v_pk_mul_f32 v[58:59], v[58:59], v[216:217]
	v_pk_mul_f32 v[60:61], v[60:61], v[218:219]
	v_pk_mul_f32 v[62:63], v[62:63], v[220:221]
	v_pk_mul_f32 v[214:215], v[44:45], s[4:5]
	v_pk_mul_f32 v[216:217], v[46:47], s[4:5]
	v_pk_mul_f32 v[218:219], v[48:49], s[4:5]
	v_pk_mul_f32 v[220:221], v[50:51], s[4:5]
	v_exp_f32_e32 v214, v214
	v_exp_f32_e32 v215, v215
; __device__ __forceinline__ float sigm(float x) { return __builtin_amdgcn_rcpf(1.0f + __expf(-x)); }
; __device__ __forceinline__ float siluf(float x) { return x * __builtin_amdgcn_rcpf(1.0f + __expf(-x)); }
;     __device__ __forceinline__ void operator()(const f32x4 (&acc)[2][2][4][2], const Unit& u, int wr, int wc, int fr, int fq) const {
;     ...
;                 for (int bj = 0; bj < 2; ++bj) { const f32x4 a0 = acc[ai][bj][m][0], a1 = acc[ai][bj][m][1];
;                     float f[8];
; #pragma unroll
;                     for (int q = 0; q < 4; ++q) { f[q] = act_silu ? siluf(a0[q]) : sigm(a0[q]); f[4 + q] = act_silu ? siluf(a1[q]) : sigm(a1[q]); }
	v_exp_f32_e32 v216, v216
	v_exp_f32_e32 v217, v217
	v_exp_f32_e32 v218, v218
	v_exp_f32_e32 v219, v219
	v_exp_f32_e32 v220, v220
	v_exp_f32_e32 v221, v221
	v_pk_add_f32 v[214:215], v[214:215], s[6:7]
	v_pk_add_f32 v[216:217], v[216:217], s[6:7]
	v_pk_add_f32 v[218:219], v[218:219], s[6:7]
	v_pk_add_f32 v[220:221], v[220:221], s[6:7]
	v_rcp_f32_e32 v214, v214
	v_rcp_f32_e32 v215, v215
	v_rcp_f32_e32 v216, v216
	v_rcp_f32_e32 v217, v217
	v_rcp_f32_e32 v218, v218
	v_rcp_f32_e32 v219, v219
	v_rcp_f32_e32 v220, v220
	v_rcp_f32_e32 v221, v221
	v_pk_mul_f32 v[44:45], v[44:45], v[214:215]
	v_pk_mul_f32 v[46:47], v[46:47], v[216:217]
	v_pk_mul_f32 v[48:49], v[48:49], v[218:219]
	v_pk_mul_f32 v[50:51], v[50:51], v[220:221]
	v_pk_mul_f32 v[214:215], v[32:33], s[4:5]
	v_pk_mul_f32 v[216:217], v[34:35], s[4:5]
	v_pk_mul_f32 v[218:219], v[36:37], s[4:5]
	v_pk_mul_f32 v[220:221], v[38:39], s[4:5]
	v_exp_f32_e32 v214, v214
	v_exp_f32_e32 v215, v215
	v_exp_f32_e32 v216, v216
	v_exp_f32_e32 v217, v217
	v_exp_f32_e32 v218, v218
	v_exp_f32_e32 v219, v219
	v_exp_f32_e32 v220, v220
	v_exp_f32_e32 v221, v221
	v_pk_add_f32 v[214:215], v[214:215], s[6:7]
	v_pk_add_f32 v[216:217], v[216:217], s[6:7]
	v_pk_add_f32 v[218:219], v[218:219], s[6:7]
	v_pk_add_f32 v[220:221], v[220:221], s[6:7]
	v_rcp_f32_e32 v214, v214
	v_rcp_f32_e32 v215, v215
	v_rcp_f32_e32 v216, v216
	v_rcp_f32_e32 v217, v217
	v_rcp_f32_e32 v218, v218
	v_rcp_f32_e32 v219, v219
	v_rcp_f32_e32 v220, v220
	v_rcp_f32_e32 v221, v221
	v_pk_mul_f32 v[32:33], v[32:33], v[214:215]
	v_pk_mul_f32 v[34:35], v[34:35], v[216:217]
	v_pk_mul_f32 v[36:37], v[36:37], v[218:219]
	v_pk_mul_f32 v[38:39], v[38:39], v[220:221]
	v_pk_mul_f32 v[214:215], v[24:25], s[4:5]
	v_pk_mul_f32 v[216:217], v[26:27], s[4:5]
	v_pk_mul_f32 v[218:219], v[28:29], s[4:5]
	v_pk_mul_f32 v[220:221], v[30:31], s[4:5]
	v_exp_f32_e32 v214, v214
	v_exp_f32_e32 v215, v215
	v_exp_f32_e32 v216, v216
	v_exp_f32_e32 v217, v217
	v_exp_f32_e32 v218, v218
	v_exp_f32_e32 v219, v219
	v_exp_f32_e32 v220, v220
	v_exp_f32_e32 v221, v221
	v_pk_add_f32 v[214:215], v[214:215], s[6:7]
	v_pk_add_f32 v[216:217], v[216:217], s[6:7]
	v_pk_add_f32 v[218:219], v[218:219], s[6:7]
	v_pk_add_f32 v[220:221], v[220:221], s[6:7]
	v_rcp_f32_e32 v214, v214
	v_rcp_f32_e32 v215, v215
	v_rcp_f32_e32 v216, v216
	v_rcp_f32_e32 v217, v217
	v_rcp_f32_e32 v218, v218
	v_rcp_f32_e32 v219, v219
	v_rcp_f32_e32 v220, v220
	v_rcp_f32_e32 v221, v221
	v_pk_mul_f32 v[24:25], v[24:25], v[214:215]
	v_pk_mul_f32 v[26:27], v[26:27], v[216:217]
	v_pk_mul_f32 v[28:29], v[28:29], v[218:219]
	v_pk_mul_f32 v[30:31], v[30:31], v[220:221]
	v_pk_mul_f32 v[214:215], v[16:17], s[4:5]
	v_pk_mul_f32 v[216:217], v[18:19], s[4:5]
	v_pk_mul_f32 v[218:219], v[20:21], s[4:5]
	v_pk_mul_f32 v[220:221], v[22:23], s[4:5]
	v_exp_f32_e32 v214, v214
	v_exp_f32_e32 v215, v215
	v_exp_f32_e32 v216, v216
	v_exp_f32_e32 v217, v217
	v_exp_f32_e32 v218, v218
	v_exp_f32_e32 v219, v219
	v_exp_f32_e32 v220, v220
	v_exp_f32_e32 v221, v221
	v_pk_add_f32 v[214:215], v[214:215], s[6:7]
	v_pk_add_f32 v[216:217], v[216:217], s[6:7]
	v_pk_add_f32 v[218:219], v[218:219], s[6:7]
	v_pk_add_f32 v[220:221], v[220:221], s[6:7]
	v_rcp_f32_e32 v214, v214
	v_rcp_f32_e32 v215, v215
	v_rcp_f32_e32 v216, v216
	v_rcp_f32_e32 v217, v217
	v_rcp_f32_e32 v218, v218
	v_rcp_f32_e32 v219, v219
	v_rcp_f32_e32 v220, v220
	v_rcp_f32_e32 v221, v221
	v_pk_mul_f32 v[16:17], v[16:17], v[214:215]
	v_pk_mul_f32 v[18:19], v[18:19], v[216:217]
	v_pk_mul_f32 v[20:21], v[20:21], v[218:219]
	v_pk_mul_f32 v[22:23], v[22:23], v[220:221]
	v_pk_mul_f32 v[214:215], v[8:9], s[4:5]
	v_pk_mul_f32 v[216:217], v[10:11], s[4:5]
	v_pk_mul_f32 v[218:219], v[12:13], s[4:5]
	v_pk_mul_f32 v[220:221], v[14:15], s[4:5]
	v_exp_f32_e32 v214, v214
	v_exp_f32_e32 v215, v215
	v_exp_f32_e32 v216, v216
	v_exp_f32_e32 v217, v217
	v_exp_f32_e32 v218, v218
	v_exp_f32_e32 v219, v219
	v_exp_f32_e32 v220, v220
	v_exp_f32_e32 v221, v221
	v_pk_add_f32 v[214:215], v[214:215], s[6:7]
	v_pk_add_f32 v[216:217], v[216:217], s[6:7]
	v_pk_add_f32 v[218:219], v[218:219], s[6:7]
	v_pk_add_f32 v[220:221], v[220:221], s[6:7]
	v_rcp_f32_e32 v214, v214
	v_rcp_f32_e32 v215, v215
	v_rcp_f32_e32 v216, v216
	v_rcp_f32_e32 v217, v217
	v_rcp_f32_e32 v218, v218
	v_rcp_f32_e32 v219, v219
	v_rcp_f32_e32 v220, v220
	v_rcp_f32_e32 v221, v221
	v_pk_mul_f32 v[8:9], v[8:9], v[214:215]
	v_pk_mul_f32 v[10:11], v[10:11], v[216:217]
	v_pk_mul_f32 v[12:13], v[12:13], v[218:219]
	v_pk_mul_f32 v[14:15], v[14:15], v[220:221]
	v_pk_mul_f32 v[214:215], v[0:1], s[4:5]
	v_pk_mul_f32 v[216:217], v[2:3], s[4:5]
	v_pk_mul_f32 v[218:219], v[4:5], s[4:5]
	v_pk_mul_f32 v[220:221], v[6:7], s[4:5]
	v_exp_f32_e32 v214, v214
	v_exp_f32_e32 v215, v215
	v_exp_f32_e32 v216, v216
	v_exp_f32_e32 v217, v217
	v_exp_f32_e32 v218, v218
	v_exp_f32_e32 v219, v219
	v_exp_f32_e32 v220, v220
	v_exp_f32_e32 v221, v221
	v_pk_add_f32 v[214:215], v[214:215], s[6:7]
	v_pk_add_f32 v[216:217], v[216:217], s[6:7]
	v_pk_add_f32 v[218:219], v[218:219], s[6:7]
	v_pk_add_f32 v[220:221], v[220:221], s[6:7]
	v_rcp_f32_e32 v214, v214
	v_rcp_f32_e32 v215, v215
	v_rcp_f32_e32 v216, v216
	v_rcp_f32_e32 v217, v217
	v_rcp_f32_e32 v218, v218
	v_rcp_f32_e32 v219, v219
	v_rcp_f32_e32 v220, v220
	v_rcp_f32_e32 v221, v221
	v_pk_mul_f32 v[0:1], v[0:1], v[214:215]
	v_pk_mul_f32 v[2:3], v[2:3], v[216:217]
	v_pk_mul_f32 v[4:5], v[4:5], v[218:219]
	v_pk_mul_f32 v[6:7], v[6:7], v[220:221]
	s_waitcnt vmcnt(15)
; __device__ __forceinline__ float bf_lo(unsigned w) { return __uint_as_float(w << 16); }
; __device__ __forceinline__ float bf_hi(unsigned w) { return __uint_as_float(w & 0xffff0000u); }
; __device__ __forceinline__ unsigned cvt_pk_bf16(float lo, float hi) { unsigned r; asm volatile("v_cvt_pk_bf16_f32 %0, %1, %2" : "=v"(r) : "v"(lo), "v"(hi)); return r; }
;     __device__ __forceinline__ void operator()(const f32x4 (&acc)[2][2][4][2], const Unit& u, int wr, int wc, int fr, int fq) const {
;     ...
;                     if (ldp) { const u32x4 o = old8[m][bj];
;                         if (recip) { f[0] *= __builtin_amdgcn_rcpf(bf_lo(o.x)); f[1] *= __builtin_amdgcn_rcpf(bf_hi(o.x)); f[2] *= __builtin_amdgcn_rcpf(bf_lo(o.y)); f[3] *= __builtin_amdgcn_rcpf(bf_hi(o.y));
;                             f[4] *= __builtin_amdgcn_rcpf(bf_lo(o.z)); f[5] *= __builtin_amdgcn_rcpf(bf_hi(o.z)); f[6] *= __builtin_amdgcn_rcpf(bf_lo(o.w)); f[7] *= __builtin_amdgcn_rcpf(bf_hi(o.w)); }
;                         else { f[0] *= bf_lo(o.x); f[1] *= bf_hi(o.x); f[2] *= bf_lo(o.y); f[3] *= bf_hi(o.y); f[4] *= bf_lo(o.z); f[5] *= bf_hi(o.z); f[6] *= bf_lo(o.w); f[7] *= bf_hi(o.w); } }
;                     u32x4 w; w.x = cvt_pk_bf16(f[0], f[1]); w.y = cvt_pk_bf16(f[2], f[3]); w.z = cvt_pk_bf16(f[4], f[5]); w.w = cvt_pk_bf16(f[6], f[7]);
;                     if (st_lm) { if (recip) __builtin_nontemporal_store(w, (u32x4*)(stp + ((ai * 4 + m) * 2 + bj) * 512)); else *(u32x4*)(stp + ((ai * 4 + m) * 2 + bj) * 512) = w; }
;                     else *(u32x4*)(stp + (size_t)(row0 + ai * 128 + m * 16) * ld + col0 + bj * 128) = w; } }
	v_lshlrev_b32_e32 v214, 16, v116
	v_and_b32_e32 v215, s1, v116
	v_lshlrev_b32_e32 v216, 16, v117
	v_and_b32_e32 v217, s1, v117
	v_lshlrev_b32_e32 v218, 16, v118
	v_and_b32_e32 v219, s1, v118
	v_lshlrev_b32_e32 v220, 16, v119
	v_and_b32_e32 v221, s1, v119
	v_pk_mul_f32 v[156:157], v[156:157], v[214:215]
	v_pk_mul_f32 v[158:159], v[158:159], v[216:217]
	v_pk_mul_f32 v[152:153], v[152:153], v[218:219]
	v_pk_mul_f32 v[154:155], v[154:155], v[220:221]
	v_cvt_pk_bf16_f32 v116, v156, v157
	v_cvt_pk_bf16_f32 v117, v158, v159
	v_cvt_pk_bf16_f32 v118, v152, v153
	v_cvt_pk_bf16_f32 v119, v154, v155
	global_store_dwordx4 v222, v[116:119], s[74:75]
	s_waitcnt vmcnt(15)
	v_lshlrev_b32_e32 v214, 16, v104
	v_and_b32_e32 v215, s1, v104
	v_lshlrev_b32_e32 v216, 16, v105
	v_and_b32_e32 v217, s1, v105
	v_lshlrev_b32_e32 v218, 16, v106
	v_and_b32_e32 v219, s1, v106
	v_lshlrev_b32_e32 v220, 16, v107
	v_and_b32_e32 v221, s1, v107
	v_pk_mul_f32 v[148:149], v[148:149], v[214:215]
	v_pk_mul_f32 v[150:151], v[150:151], v[216:217]
	v_pk_mul_f32 v[144:145], v[144:145], v[218:219]
	v_pk_mul_f32 v[146:147], v[146:147], v[220:221]
	v_cvt_pk_bf16_f32 v104, v148, v149
	v_cvt_pk_bf16_f32 v105, v150, v151
	v_cvt_pk_bf16_f32 v106, v144, v145
	v_cvt_pk_bf16_f32 v107, v146, v147
	global_store_dwordx4 v222, v[104:107], s[74:75] offset:256
	s_waitcnt vmcnt(15)
	v_lshlrev_b32_e32 v214, 16, v92
	v_and_b32_e32 v215, s1, v92
	v_lshlrev_b32_e32 v216, 16, v93
	v_and_b32_e32 v217, s1, v93
	v_lshlrev_b32_e32 v218, 16, v94
	v_and_b32_e32 v219, s1, v94
	v_lshlrev_b32_e32 v220, 16, v95
	v_and_b32_e32 v221, s1, v95
	v_pk_mul_f32 v[140:141], v[140:141], v[214:215]
	v_pk_mul_f32 v[142:143], v[142:143], v[216:217]
	v_pk_mul_f32 v[136:137], v[136:137], v[218:219]
	v_pk_mul_f32 v[138:139], v[138:139], v[220:221]
	v_cvt_pk_bf16_f32 v92, v140, v141
	v_cvt_pk_bf16_f32 v93, v142, v143
	v_cvt_pk_bf16_f32 v94, v136, v137
	v_cvt_pk_bf16_f32 v95, v138, v139
	v_add_u32_e32 v223, 0x8000, v222
	global_store_dwordx4 v223, v[92:95], s[74:75]
	s_waitcnt vmcnt(15)
	v_lshlrev_b32_e32 v214, 16, v80
	v_and_b32_e32 v215, s1, v80
	v_lshlrev_b32_e32 v216, 16, v81
	v_and_b32_e32 v217, s1, v81
	v_lshlrev_b32_e32 v218, 16, v82
	v_and_b32_e32 v219, s1, v82
	v_lshlrev_b32_e32 v220, 16, v83
	v_and_b32_e32 v221, s1, v83
	v_pk_mul_f32 v[132:133], v[132:133], v[214:215]
	v_pk_mul_f32 v[134:135], v[134:135], v[216:217]
	v_pk_mul_f32 v[128:129], v[128:129], v[218:219]
	v_pk_mul_f32 v[130:131], v[130:131], v[220:221]
	v_cvt_pk_bf16_f32 v80, v132, v133
	v_cvt_pk_bf16_f32 v81, v134, v135
	v_cvt_pk_bf16_f32 v82, v128, v129
	v_cvt_pk_bf16_f32 v83, v130, v131
	global_store_dwordx4 v223, v[80:83], s[74:75] offset:256
	s_waitcnt vmcnt(15)
	v_lshlrev_b32_e32 v214, 16, v76
	v_and_b32_e32 v215, s1, v76
	v_lshlrev_b32_e32 v216, 16, v77
	v_and_b32_e32 v217, s1, v77
	v_lshlrev_b32_e32 v218, 16, v78
	v_and_b32_e32 v219, s1, v78
	v_lshlrev_b32_e32 v220, 16, v79
	v_and_b32_e32 v221, s1, v79
	v_pk_mul_f32 v[124:125], v[124:125], v[214:215]
	v_pk_mul_f32 v[126:127], v[126:127], v[216:217]
	v_pk_mul_f32 v[120:121], v[120:121], v[218:219]
	v_pk_mul_f32 v[122:123], v[122:123], v[220:221]
	v_cvt_pk_bf16_f32 v76, v124, v125
	v_cvt_pk_bf16_f32 v77, v126, v127
	v_cvt_pk_bf16_f32 v78, v120, v121
	v_cvt_pk_bf16_f32 v79, v122, v123
	v_add_u32_e32 v205, 0x10000, v222
	global_store_dwordx4 v205, v[76:79], s[74:75]
	s_waitcnt vmcnt(15)
	v_lshlrev_b32_e32 v214, 16, v64
	v_and_b32_e32 v215, s1, v64
	v_lshlrev_b32_e32 v216, 16, v65
	v_and_b32_e32 v217, s1, v65
	v_lshlrev_b32_e32 v218, 16, v66
	v_and_b32_e32 v219, s1, v66
	v_lshlrev_b32_e32 v220, 16, v67
	v_and_b32_e32 v221, s1, v67
	v_pk_mul_f32 v[112:113], v[112:113], v[214:215]
	v_pk_mul_f32 v[114:115], v[114:115], v[216:217]
	v_pk_mul_f32 v[108:109], v[108:109], v[218:219]
	v_pk_mul_f32 v[110:111], v[110:111], v[220:221]
	v_cvt_pk_bf16_f32 v64, v112, v113
	v_cvt_pk_bf16_f32 v65, v114, v115
	v_cvt_pk_bf16_f32 v66, v108, v109
	v_cvt_pk_bf16_f32 v67, v110, v111
	global_store_dwordx4 v205, v[64:67], s[74:75] offset:256
	s_waitcnt vmcnt(15)
	v_lshlrev_b32_e32 v214, 16, v52
	v_and_b32_e32 v215, s1, v52
	v_lshlrev_b32_e32 v216, 16, v53
	v_and_b32_e32 v217, s1, v53
	v_lshlrev_b32_e32 v218, 16, v54
	v_and_b32_e32 v219, s1, v54
	v_lshlrev_b32_e32 v220, 16, v55
	v_and_b32_e32 v221, s1, v55
	v_pk_mul_f32 v[100:101], v[100:101], v[214:215]
	v_pk_mul_f32 v[102:103], v[102:103], v[216:217]
	v_pk_mul_f32 v[96:97], v[96:97], v[218:219]
	v_pk_mul_f32 v[98:99], v[98:99], v[220:221]
	v_cvt_pk_bf16_f32 v52, v100, v101
	v_cvt_pk_bf16_f32 v53, v102, v103
	v_cvt_pk_bf16_f32 v54, v96, v97
	v_cvt_pk_bf16_f32 v55, v98, v99
	v_add_u32_e32 v223, 0x18000, v222
	global_store_dwordx4 v223, v[52:55], s[74:75]
	s_waitcnt vmcnt(15)
	v_lshlrev_b32_e32 v214, 16, v40
	v_and_b32_e32 v215, s1, v40
	v_lshlrev_b32_e32 v216, 16, v41
	v_and_b32_e32 v217, s1, v41
	v_lshlrev_b32_e32 v218, 16, v42
	v_and_b32_e32 v219, s1, v42
	v_lshlrev_b32_e32 v220, 16, v43
	v_and_b32_e32 v221, s1, v43
	v_pk_mul_f32 v[88:89], v[88:89], v[214:215]
	v_pk_mul_f32 v[90:91], v[90:91], v[216:217]
	v_pk_mul_f32 v[84:85], v[84:85], v[218:219]
	v_pk_mul_f32 v[86:87], v[86:87], v[220:221]
	v_cvt_pk_bf16_f32 v40, v88, v89
	v_cvt_pk_bf16_f32 v41, v90, v91
	v_cvt_pk_bf16_f32 v42, v84, v85
	v_cvt_pk_bf16_f32 v43, v86, v87
	global_store_dwordx4 v223, v[40:43], s[74:75] offset:256
	s_waitcnt vmcnt(15)
; __device__ __forceinline__ float bf_lo(unsigned w) { return __uint_as_float(w << 16); }
; __device__ __forceinline__ float bf_hi(unsigned w) { return __uint_as_float(w & 0xffff0000u); }
; __device__ __forceinline__ unsigned cvt_pk_bf16(float lo, float hi) { unsigned r; asm volatile("v_cvt_pk_bf16_f32 %0, %1, %2" : "=v"(r) : "v"(lo), "v"(hi)); return r; }
;     __device__ __forceinline__ void operator()(const f32x4 (&acc)[2][2][4][2], const Unit& u, int wr, int wc, int fr, int fq) const {
;     ...
;                     if (ldp) { const u32x4 o = old8[m][bj];
;                         if (recip) { f[0] *= __builtin_amdgcn_rcpf(bf_lo(o.x)); f[1] *= __builtin_amdgcn_rcpf(bf_hi(o.x)); f[2] *= __builtin_amdgcn_rcpf(bf_lo(o.y)); f[3] *= __builtin_amdgcn_rcpf(bf_hi(o.y));
;                             f[4] *= __builtin_amdgcn_rcpf(bf_lo(o.z)); f[5] *= __builtin_amdgcn_rcpf(bf_hi(o.z)); f[6] *= __builtin_amdgcn_rcpf(bf_lo(o.w)); f[7] *= __builtin_amdgcn_rcpf(bf_hi(o.w)); }
;                         else { f[0] *= bf_lo(o.x); f[1] *= bf_hi(o.x); f[2] *= bf_lo(o.y); f[3] *= bf_hi(o.y); f[4] *= bf_lo(o.z); f[5] *= bf_hi(o.z); f[6] *= bf_lo(o.w); f[7] *= bf_hi(o.w); } }
;                     u32x4 w; w.x = cvt_pk_bf16(f[0], f[1]); w.y = cvt_pk_bf16(f[2], f[3]); w.z = cvt_pk_bf16(f[4], f[5]); w.w = cvt_pk_bf16(f[6], f[7]);
;                     if (st_lm) { if (recip) __builtin_nontemporal_store(w, (u32x4*)(stp + ((ai * 4 + m) * 2 + bj) * 512)); else *(u32x4*)(stp + ((ai * 4 + m) * 2 + bj) * 512) = w; }
;                     else *(u32x4*)(stp + (size_t)(row0 + ai * 128 + m * 16) * ld + col0 + bj * 128) = w; } }
	v_lshlrev_b32_e32 v214, 16, v228
	v_and_b32_e32 v215, s1, v228
	v_lshlrev_b32_e32 v216, 16, v229
	v_and_b32_e32 v217, s1, v229
	v_lshlrev_b32_e32 v218, 16, v230
	v_and_b32_e32 v219, s1, v230
	v_lshlrev_b32_e32 v220, 16, v231
	v_and_b32_e32 v221, s1, v231
	v_pk_mul_f32 v[72:73], v[72:73], v[214:215]
	v_pk_mul_f32 v[74:75], v[74:75], v[216:217]
	v_pk_mul_f32 v[68:69], v[68:69], v[218:219]
	v_pk_mul_f32 v[70:71], v[70:71], v[220:221]
	v_cvt_pk_bf16_f32 v228, v72, v73
	v_cvt_pk_bf16_f32 v229, v74, v75
	v_cvt_pk_bf16_f32 v230, v68, v69
	v_cvt_pk_bf16_f32 v231, v70, v71
	v_add_u32_e32 v205, 0x40000, v222
	global_store_dwordx4 v205, v[228:231], s[74:75]
	s_waitcnt vmcnt(15)
	v_lshlrev_b32_e32 v214, 16, v232
	v_and_b32_e32 v215, s1, v232
	v_lshlrev_b32_e32 v216, 16, v233
	v_and_b32_e32 v217, s1, v233
	v_lshlrev_b32_e32 v218, 16, v234
	v_and_b32_e32 v219, s1, v234
	v_lshlrev_b32_e32 v220, 16, v235
	v_and_b32_e32 v221, s1, v235
	v_pk_mul_f32 v[60:61], v[60:61], v[214:215]
	v_pk_mul_f32 v[62:63], v[62:63], v[216:217]
	v_pk_mul_f32 v[56:57], v[56:57], v[218:219]
	v_pk_mul_f32 v[58:59], v[58:59], v[220:221]
	v_cvt_pk_bf16_f32 v232, v60, v61
	v_cvt_pk_bf16_f32 v233, v62, v63
	v_cvt_pk_bf16_f32 v234, v56, v57
	v_cvt_pk_bf16_f32 v235, v58, v59
	global_store_dwordx4 v205, v[232:235], s[74:75] offset:256
	s_waitcnt vmcnt(15)
	v_lshlrev_b32_e32 v214, 16, v236
	v_and_b32_e32 v215, s1, v236
	v_lshlrev_b32_e32 v216, 16, v237
	v_and_b32_e32 v217, s1, v237
	v_lshlrev_b32_e32 v218, 16, v238
	v_and_b32_e32 v219, s1, v238
	v_lshlrev_b32_e32 v220, 16, v239
	v_and_b32_e32 v221, s1, v239
	v_pk_mul_f32 v[48:49], v[48:49], v[214:215]
	v_pk_mul_f32 v[50:51], v[50:51], v[216:217]
	v_pk_mul_f32 v[44:45], v[44:45], v[218:219]
	v_pk_mul_f32 v[46:47], v[46:47], v[220:221]
	v_cvt_pk_bf16_f32 v236, v48, v49
	v_cvt_pk_bf16_f32 v237, v50, v51
	v_cvt_pk_bf16_f32 v238, v44, v45
	v_cvt_pk_bf16_f32 v239, v46, v47
	v_add_u32_e32 v223, 0x48000, v222
	global_store_dwordx4 v223, v[236:239], s[74:75]
	s_waitcnt vmcnt(15)
	v_lshlrev_b32_e32 v214, 16, v240
	v_and_b32_e32 v215, s1, v240
	v_lshlrev_b32_e32 v216, 16, v241
	v_and_b32_e32 v217, s1, v241
	v_lshlrev_b32_e32 v218, 16, v242
	v_and_b32_e32 v219, s1, v242
	v_lshlrev_b32_e32 v220, 16, v243
	v_and_b32_e32 v221, s1, v243
	v_pk_mul_f32 v[36:37], v[36:37], v[214:215]
	v_pk_mul_f32 v[38:39], v[38:39], v[216:217]
	v_pk_mul_f32 v[32:33], v[32:33], v[218:219]
	v_pk_mul_f32 v[34:35], v[34:35], v[220:221]
	v_cvt_pk_bf16_f32 v240, v36, v37
	v_cvt_pk_bf16_f32 v241, v38, v39
	v_cvt_pk_bf16_f32 v242, v32, v33
	v_cvt_pk_bf16_f32 v243, v34, v35
	global_store_dwordx4 v223, v[240:243], s[74:75] offset:256
	s_waitcnt vmcnt(15)
	v_lshlrev_b32_e32 v214, 16, v244
	v_and_b32_e32 v215, s1, v244
	v_lshlrev_b32_e32 v216, 16, v245
	v_and_b32_e32 v217, s1, v245
	v_lshlrev_b32_e32 v218, 16, v246
	v_and_b32_e32 v219, s1, v246
	v_lshlrev_b32_e32 v220, 16, v247
	v_and_b32_e32 v221, s1, v247
	v_pk_mul_f32 v[28:29], v[28:29], v[214:215]
	v_pk_mul_f32 v[30:31], v[30:31], v[216:217]
	v_pk_mul_f32 v[24:25], v[24:25], v[218:219]
	v_pk_mul_f32 v[26:27], v[26:27], v[220:221]
	v_cvt_pk_bf16_f32 v244, v28, v29
	v_cvt_pk_bf16_f32 v245, v30, v31
	v_cvt_pk_bf16_f32 v246, v24, v25
	v_cvt_pk_bf16_f32 v247, v26, v27
	v_add_u32_e32 v205, 0x50000, v222
	global_store_dwordx4 v205, v[244:247], s[74:75]
	s_waitcnt vmcnt(15)
	v_lshlrev_b32_e32 v214, 16, v248
	v_and_b32_e32 v215, s1, v248
	v_lshlrev_b32_e32 v216, 16, v249
	v_and_b32_e32 v217, s1, v249
	v_lshlrev_b32_e32 v218, 16, v250
	v_and_b32_e32 v219, s1, v250
	v_lshlrev_b32_e32 v220, 16, v251
	v_and_b32_e32 v221, s1, v251
	v_pk_mul_f32 v[20:21], v[20:21], v[214:215]
	v_pk_mul_f32 v[22:23], v[22:23], v[216:217]
	v_pk_mul_f32 v[16:17], v[16:17], v[218:219]
	v_pk_mul_f32 v[18:19], v[18:19], v[220:221]
	v_cvt_pk_bf16_f32 v248, v20, v21
	v_cvt_pk_bf16_f32 v249, v22, v23
	v_cvt_pk_bf16_f32 v250, v16, v17
	v_cvt_pk_bf16_f32 v251, v18, v19
	global_store_dwordx4 v205, v[248:251], s[74:75] offset:256
	s_waitcnt vmcnt(15)
	v_lshlrev_b32_e32 v214, 16, v206
	v_and_b32_e32 v215, s1, v206
	v_lshlrev_b32_e32 v216, 16, v207
	v_and_b32_e32 v217, s1, v207
	v_lshlrev_b32_e32 v218, 16, v208
	v_and_b32_e32 v219, s1, v208
	v_lshlrev_b32_e32 v220, 16, v209
	v_and_b32_e32 v221, s1, v209
	v_pk_mul_f32 v[12:13], v[12:13], v[214:215]
	v_pk_mul_f32 v[14:15], v[14:15], v[216:217]
	v_pk_mul_f32 v[8:9], v[8:9], v[218:219]
	v_pk_mul_f32 v[10:11], v[10:11], v[220:221]
	v_cvt_pk_bf16_f32 v206, v12, v13
	v_cvt_pk_bf16_f32 v207, v14, v15
	v_cvt_pk_bf16_f32 v208, v8, v9
	v_cvt_pk_bf16_f32 v209, v10, v11
	v_add_u32_e32 v223, 0x58000, v222
	global_store_dwordx4 v223, v[206:209], s[74:75]
	s_waitcnt vmcnt(15)
	v_lshlrev_b32_e32 v214, 16, v210
	v_and_b32_e32 v215, s1, v210
	v_lshlrev_b32_e32 v216, 16, v211
	v_and_b32_e32 v217, s1, v211
	v_lshlrev_b32_e32 v218, 16, v212
	v_and_b32_e32 v219, s1, v212
	v_lshlrev_b32_e32 v220, 16, v213
	v_and_b32_e32 v221, s1, v213
	v_pk_mul_f32 v[4:5], v[4:5], v[214:215]
	v_pk_mul_f32 v[6:7], v[6:7], v[216:217]
	v_pk_mul_f32 v[0:1], v[0:1], v[218:219]
	v_pk_mul_f32 v[2:3], v[2:3], v[220:221]
	v_cvt_pk_bf16_f32 v210, v4, v5
	v_cvt_pk_bf16_f32 v211, v6, v7
	v_cvt_pk_bf16_f32 v212, v0, v1
	v_cvt_pk_bf16_f32 v213, v2, v3
	global_store_dwordx4 v223, v[210:213], s[74:75] offset:256
	s_branch .LBB0_727
; __device__ __forceinline__ float sigm(float x) { return __builtin_amdgcn_rcpf(1.0f + __expf(-x)); }
; __device__ __forceinline__ float siluf(float x) { return x * __builtin_amdgcn_rcpf(1.0f + __expf(-x)); }
;     __device__ __forceinline__ void operator()(const f32x4 (&acc)[2][2][4][2], const Unit& u, int wr, int wc, int fr, int fq) const {
;     ...
;         const int gl_off = ((wr * 4 + wc) * 16 * 64 + (fq * 16 + fr)) * 8;
;         const int row0 = u.pm * 256 + wr * 64 + fr, col0 = wc * 32 + 8 * fq;
;         const bf16_t* ldp = nullptr; bf16_t* stp; bool ld_lm = false, st_lm = false, act_silu = false, recip = false; int ld = 0;
;         if (wt < 16) { bf16_t* t = (bf16_t*)(ws + OFF_Q) + (size_t)(u.pm * 4 + (wt - 12)) * 65536 + gl_off; ldp = t; stp = t; ld_lm = st_lm = true; }
;         else if (wt < 20) { ldp = (const bf16_t*)(ws + OFF_Q) + (size_t)(u.pm * 4 + (wt - 16)) * 65536 + gl_off; ld_lm = true; stp = am + (wt - 16) * 256; ld = 1024; act_silu = true; }
;         else if (wt < 24) { bf16_t* t = (bf16_t*)(ws + OFF_PM) + (wt - 22) * 256; ldp = t; stp = t; ld = 512; act_silu = true; }
;         else if (wt < 28) { stp = (bf16_t*)(ws + OFF_GB) + (size_t)(u.pm * 8 + (wt - 24)) * 65536 + gl_off; st_lm = true; }
;         else { bf16_t* t = (bf16_t*)(ws + OFF_GB) + (size_t)(u.pm * 8 + (wt - 24)) * 65536 + gl_off; stp = t; st_lm = true; ldp = t - 4 * 65536; ld_lm = true; recip = true; }
; #pragma unroll
;         for (int ai = 0; ai < 2; ++ai) {
;             u32x4 old8[4][2];
;             if (ldp) {
; #pragma unroll
;                 for (int m = 0; m < 4; ++m)
; #pragma unroll
;                     for (int bj = 0; bj < 2; ++bj) old8[m][bj] = ld_lm ? *(const u32x4*)(ldp + ((ai * 4 + m) * 2 + bj) * 512)
;                                                                        : *(const u32x4*)(ldp + (size_t)(row0 + ai * 128 + m * 16) * ld + col0 + bj * 128);
;             }
; #pragma unroll
;             for (int m = 0; m < 4; ++m)
; #pragma unroll
;                 for (int bj = 0; bj < 2; ++bj) { const f32x4 a0 = acc[ai][bj][m][0], a1 = acc[ai][bj][m][1];
;                     float f[8];
; #pragma unroll
;                     for (int q = 0; q < 4; ++q) { f[q] = act_silu ? siluf(a0[q]) : sigm(a0[q]); f[4 + q] = act_silu ? siluf(a1[q]) : sigm(a1[q]); }
.Lep5_o:
	s_add_i32 s60, s89, s38
	s_ashr_i32 s61, s60, 31
	s_lshl_b64 s[60:61], s[60:61], 17
	v_lshl_add_u64 v[196:197], v[176:177], 0, s[60:61]
	v_lshl_add_u64 v[198:199], v[196:197], 0, s[2:3]
	v_lshl_add_u64 v[200:201], v[198:199], 0, s[2:3]
	v_lshl_add_u64 v[202:203], v[200:201], 0, s[2:3]
	global_load_dwordx4 v[116:119], v[196:197], off
	global_load_dwordx4 v[104:107], v[196:197], off offset:1024
	global_load_dwordx4 v[92:95], v[196:197], off offset:2048
	global_load_dwordx4 v[80:83], v[196:197], off offset:3072
	global_load_dwordx4 v[76:79], v[198:199], off
	global_load_dwordx4 v[64:67], v[198:199], off offset:1024
	global_load_dwordx4 v[52:55], v[198:199], off offset:2048
	global_load_dwordx4 v[40:43], v[198:199], off offset:3072
	global_load_dwordx4 v[228:231], v[200:201], off
	global_load_dwordx4 v[232:235], v[200:201], off offset:1024
	global_load_dwordx4 v[236:239], v[200:201], off offset:2048
	global_load_dwordx4 v[240:243], v[200:201], off offset:3072
	global_load_dwordx4 v[244:247], v[202:203], off
	global_load_dwordx4 v[248:251], v[202:203], off offset:1024
	global_load_dwordx4 v[206:209], v[202:203], off offset:2048
	global_load_dwordx4 v[210:213], v[202:203], off offset:3072
	v_pk_mul_f32 v[214:215], v[152:153], s[4:5]
	v_pk_mul_f32 v[216:217], v[154:155], s[4:5]
	v_pk_mul_f32 v[218:219], v[156:157], s[4:5]
	v_pk_mul_f32 v[220:221], v[158:159], s[4:5]
	v_exp_f32_e32 v214, v214
	v_exp_f32_e32 v215, v215
	v_exp_f32_e32 v216, v216
	v_exp_f32_e32 v217, v217
	v_exp_f32_e32 v218, v218
	v_exp_f32_e32 v219, v219
	v_exp_f32_e32 v220, v220
	v_exp_f32_e32 v221, v221
	v_pk_add_f32 v[214:215], v[214:215], s[6:7]
	v_pk_add_f32 v[216:217], v[216:217], s[6:7]
	v_pk_add_f32 v[218:219], v[218:219], s[6:7]
	v_pk_add_f32 v[220:221], v[220:221], s[6:7]
	v_rcp_f32_e32 v152, v214
	v_rcp_f32_e32 v153, v215
	v_rcp_f32_e32 v154, v216
	v_rcp_f32_e32 v155, v217
	v_rcp_f32_e32 v156, v218
	v_rcp_f32_e32 v157, v219
	v_rcp_f32_e32 v158, v220
	v_rcp_f32_e32 v159, v221
	v_pk_mul_f32 v[214:215], v[144:145], s[4:5]
	v_pk_mul_f32 v[216:217], v[146:147], s[4:5]
	v_pk_mul_f32 v[218:219], v[148:149], s[4:5]
	v_pk_mul_f32 v[220:221], v[150:151], s[4:5]
	v_exp_f32_e32 v214, v214
	v_exp_f32_e32 v215, v215
	v_exp_f32_e32 v216, v216
	v_exp_f32_e32 v217, v217
	v_exp_f32_e32 v218, v218
	v_exp_f32_e32 v219, v219
	v_exp_f32_e32 v220, v220
	v_exp_f32_e32 v221, v221
	v_pk_add_f32 v[214:215], v[214:215], s[6:7]
	v_pk_add_f32 v[216:217], v[216:217], s[6:7]
	v_pk_add_f32 v[218:219], v[218:219], s[6:7]
	v_pk_add_f32 v[220:221], v[220:221], s[6:7]
	v_rcp_f32_e32 v144, v214
	v_rcp_f32_e32 v145, v215
	v_rcp_f32_e32 v146, v216
	v_rcp_f32_e32 v147, v217
	v_rcp_f32_e32 v148, v218
	v_rcp_f32_e32 v149, v219
	v_rcp_f32_e32 v150, v220
	v_rcp_f32_e32 v151, v221
	v_pk_mul_f32 v[214:215], v[136:137], s[4:5]
	v_pk_mul_f32 v[216:217], v[138:139], s[4:5]
	v_pk_mul_f32 v[218:219], v[140:141], s[4:5]
	v_pk_mul_f32 v[220:221], v[142:143], s[4:5]
	v_exp_f32_e32 v214, v214
	v_exp_f32_e32 v215, v215
	v_exp_f32_e32 v216, v216
	v_exp_f32_e32 v217, v217
	v_exp_f32_e32 v218, v218
	v_exp_f32_e32 v219, v219
	v_exp_f32_e32 v220, v220
	v_exp_f32_e32 v221, v221
	v_pk_add_f32 v[214:215], v[214:215], s[6:7]
	v_pk_add_f32 v[216:217], v[216:217], s[6:7]
	v_pk_add_f32 v[218:219], v[218:219], s[6:7]
	v_pk_add_f32 v[220:221], v[220:221], s[6:7]
	v_rcp_f32_e32 v136, v214
	v_rcp_f32_e32 v137, v215
	v_rcp_f32_e32 v138, v216
	v_rcp_f32_e32 v139, v217
	v_rcp_f32_e32 v140, v218
	v_rcp_f32_e32 v141, v219
	v_rcp_f32_e32 v142, v220
	v_rcp_f32_e32 v143, v221
	v_pk_mul_f32 v[214:215], v[128:129], s[4:5]
	v_pk_mul_f32 v[216:217], v[130:131], s[4:5]
	v_pk_mul_f32 v[218:219], v[132:133], s[4:5]
	v_pk_mul_f32 v[220:221], v[134:135], s[4:5]
	v_exp_f32_e32 v214, v214
	v_exp_f32_e32 v215, v215
	v_exp_f32_e32 v216, v216
	v_exp_f32_e32 v217, v217
	v_exp_f32_e32 v218, v218
	v_exp_f32_e32 v219, v219
	v_exp_f32_e32 v220, v220
	v_exp_f32_e32 v221, v221
	v_pk_add_f32 v[214:215], v[214:215], s[6:7]
	v_pk_add_f32 v[216:217], v[216:217], s[6:7]
	v_pk_add_f32 v[218:219], v[218:219], s[6:7]
	v_pk_add_f32 v[220:221], v[220:221], s[6:7]
	v_rcp_f32_e32 v128, v214
	v_rcp_f32_e32 v129, v215
	v_rcp_f32_e32 v130, v216
	v_rcp_f32_e32 v131, v217
	v_rcp_f32_e32 v132, v218
	v_rcp_f32_e32 v133, v219
	v_rcp_f32_e32 v134, v220
	v_rcp_f32_e32 v135, v221
	v_pk_mul_f32 v[214:215], v[120:121], s[4:5]
	v_pk_mul_f32 v[216:217], v[122:123], s[4:5]
	v_pk_mul_f32 v[218:219], v[124:125], s[4:5]
	v_pk_mul_f32 v[220:221], v[126:127], s[4:5]
	v_exp_f32_e32 v214, v214
	v_exp_f32_e32 v215, v215
	v_exp_f32_e32 v216, v216
	v_exp_f32_e32 v217, v217
	v_exp_f32_e32 v218, v218
	v_exp_f32_e32 v219, v219
	v_exp_f32_e32 v220, v220
	v_exp_f32_e32 v221, v221
	v_pk_add_f32 v[214:215], v[214:215], s[6:7]
	v_pk_add_f32 v[216:217], v[216:217], s[6:7]
	v_pk_add_f32 v[218:219], v[218:219], s[6:7]
	v_pk_add_f32 v[220:221], v[220:221], s[6:7]
	v_rcp_f32_e32 v120, v214
	v_rcp_f32_e32 v121, v215
	v_rcp_f32_e32 v122, v216
	v_rcp_f32_e32 v123, v217
	v_rcp_f32_e32 v124, v218
	v_rcp_f32_e32 v125, v219
	v_rcp_f32_e32 v126, v220
	v_rcp_f32_e32 v127, v221
	v_pk_mul_f32 v[214:215], v[108:109], s[4:5]
	v_pk_mul_f32 v[216:217], v[110:111], s[4:5]
	v_pk_mul_f32 v[218:219], v[112:113], s[4:5]
	v_pk_mul_f32 v[220:221], v[114:115], s[4:5]
	v_exp_f32_e32 v214, v214
	v_exp_f32_e32 v215, v215
	v_exp_f32_e32 v216, v216
	v_exp_f32_e32 v217, v217
	v_exp_f32_e32 v218, v218
	v_exp_f32_e32 v219, v219
	v_exp_f32_e32 v220, v220
	v_exp_f32_e32 v221, v221
	v_pk_add_f32 v[214:215], v[214:215], s[6:7]
	v_pk_add_f32 v[216:217], v[216:217], s[6:7]
	v_pk_add_f32 v[218:219], v[218:219], s[6:7]
	v_pk_add_f32 v[220:221], v[220:221], s[6:7]
; __device__ __forceinline__ float sigm(float x) { return __builtin_amdgcn_rcpf(1.0f + __expf(-x)); }
; __device__ __forceinline__ float siluf(float x) { return x * __builtin_amdgcn_rcpf(1.0f + __expf(-x)); }
;     __device__ __forceinline__ void operator()(const f32x4 (&acc)[2][2][4][2], const Unit& u, int wr, int wc, int fr, int fq) const {
;     ...
;                 for (int bj = 0; bj < 2; ++bj) { const f32x4 a0 = acc[ai][bj][m][0], a1 = acc[ai][bj][m][1];
;                     float f[8];
; #pragma unroll
;                     for (int q = 0; q < 4; ++q) { f[q] = act_silu ? siluf(a0[q]) : sigm(a0[q]); f[4 + q] = act_silu ? siluf(a1[q]) : sigm(a1[q]); }
	v_rcp_f32_e32 v108, v214
	v_rcp_f32_e32 v109, v215
	v_rcp_f32_e32 v110, v216
	v_rcp_f32_e32 v111, v217
	v_rcp_f32_e32 v112, v218
	v_rcp_f32_e32 v113, v219
	v_rcp_f32_e32 v114, v220
	v_rcp_f32_e32 v115, v221
	v_pk_mul_f32 v[214:215], v[96:97], s[4:5]
	v_pk_mul_f32 v[216:217], v[98:99], s[4:5]
	v_pk_mul_f32 v[218:219], v[100:101], s[4:5]
	v_pk_mul_f32 v[220:221], v[102:103], s[4:5]
	v_exp_f32_e32 v214, v214
	v_exp_f32_e32 v215, v215
	v_exp_f32_e32 v216, v216
	v_exp_f32_e32 v217, v217
	v_exp_f32_e32 v218, v218
	v_exp_f32_e32 v219, v219
	v_exp_f32_e32 v220, v220
	v_exp_f32_e32 v221, v221
	v_pk_add_f32 v[214:215], v[214:215], s[6:7]
	v_pk_add_f32 v[216:217], v[216:217], s[6:7]
	v_pk_add_f32 v[218:219], v[218:219], s[6:7]
	v_pk_add_f32 v[220:221], v[220:221], s[6:7]
	v_rcp_f32_e32 v96, v214
	v_rcp_f32_e32 v97, v215
	v_rcp_f32_e32 v98, v216
	v_rcp_f32_e32 v99, v217
	v_rcp_f32_e32 v100, v218
	v_rcp_f32_e32 v101, v219
	v_rcp_f32_e32 v102, v220
	v_rcp_f32_e32 v103, v221
	v_pk_mul_f32 v[214:215], v[84:85], s[4:5]
	v_pk_mul_f32 v[216:217], v[86:87], s[4:5]
	v_pk_mul_f32 v[218:219], v[88:89], s[4:5]
	v_pk_mul_f32 v[220:221], v[90:91], s[4:5]
	v_exp_f32_e32 v214, v214
	v_exp_f32_e32 v215, v215
	v_exp_f32_e32 v216, v216
	v_exp_f32_e32 v217, v217
	v_exp_f32_e32 v218, v218
	v_exp_f32_e32 v219, v219
	v_exp_f32_e32 v220, v220
	v_exp_f32_e32 v221, v221
	v_pk_add_f32 v[214:215], v[214:215], s[6:7]
	v_pk_add_f32 v[216:217], v[216:217], s[6:7]
	v_pk_add_f32 v[218:219], v[218:219], s[6:7]
	v_pk_add_f32 v[220:221], v[220:221], s[6:7]
	v_rcp_f32_e32 v84, v214
	v_rcp_f32_e32 v85, v215
	v_rcp_f32_e32 v86, v216
	v_rcp_f32_e32 v87, v217
	v_rcp_f32_e32 v88, v218
	v_rcp_f32_e32 v89, v219
	v_rcp_f32_e32 v90, v220
	v_rcp_f32_e32 v91, v221
	v_pk_mul_f32 v[214:215], v[68:69], s[4:5]
	v_pk_mul_f32 v[216:217], v[70:71], s[4:5]
	v_pk_mul_f32 v[218:219], v[72:73], s[4:5]
	v_pk_mul_f32 v[220:221], v[74:75], s[4:5]
	v_exp_f32_e32 v214, v214
	v_exp_f32_e32 v215, v215
	v_exp_f32_e32 v216, v216
	v_exp_f32_e32 v217, v217
	v_exp_f32_e32 v218, v218
	v_exp_f32_e32 v219, v219
	v_exp_f32_e32 v220, v220
	v_exp_f32_e32 v221, v221
	v_pk_add_f32 v[214:215], v[214:215], s[6:7]
	v_pk_add_f32 v[216:217], v[216:217], s[6:7]
	v_pk_add_f32 v[218:219], v[218:219], s[6:7]
	v_pk_add_f32 v[220:221], v[220:221], s[6:7]
	v_rcp_f32_e32 v68, v214
	v_rcp_f32_e32 v69, v215
	v_rcp_f32_e32 v70, v216
	v_rcp_f32_e32 v71, v217
	v_rcp_f32_e32 v72, v218
	v_rcp_f32_e32 v73, v219
	v_rcp_f32_e32 v74, v220
	v_rcp_f32_e32 v75, v221
	v_pk_mul_f32 v[214:215], v[56:57], s[4:5]
	v_pk_mul_f32 v[216:217], v[58:59], s[4:5]
	v_pk_mul_f32 v[218:219], v[60:61], s[4:5]
	v_pk_mul_f32 v[220:221], v[62:63], s[4:5]
	v_exp_f32_e32 v214, v214
	v_exp_f32_e32 v215, v215
	v_exp_f32_e32 v216, v216
	v_exp_f32_e32 v217, v217
	v_exp_f32_e32 v218, v218
	v_exp_f32_e32 v219, v219
	v_exp_f32_e32 v220, v220
	v_exp_f32_e32 v221, v221
	v_pk_add_f32 v[214:215], v[214:215], s[6:7]
	v_pk_add_f32 v[216:217], v[216:217], s[6:7]
	v_pk_add_f32 v[218:219], v[218:219], s[6:7]
	v_pk_add_f32 v[220:221], v[220:221], s[6:7]
	v_rcp_f32_e32 v56, v214
	v_rcp_f32_e32 v57, v215
	v_rcp_f32_e32 v58, v216
	v_rcp_f32_e32 v59, v217
	v_rcp_f32_e32 v60, v218
	v_rcp_f32_e32 v61, v219
	v_rcp_f32_e32 v62, v220
	v_rcp_f32_e32 v63, v221
	v_pk_mul_f32 v[214:215], v[44:45], s[4:5]
	v_pk_mul_f32 v[216:217], v[46:47], s[4:5]
	v_pk_mul_f32 v[218:219], v[48:49], s[4:5]
	v_pk_mul_f32 v[220:221], v[50:51], s[4:5]
	v_exp_f32_e32 v214, v214
	v_exp_f32_e32 v215, v215
	v_exp_f32_e32 v216, v216
	v_exp_f32_e32 v217, v217
	v_exp_f32_e32 v218, v218
	v_exp_f32_e32 v219, v219
	v_exp_f32_e32 v220, v220
	v_exp_f32_e32 v221, v221
	v_pk_add_f32 v[214:215], v[214:215], s[6:7]
	v_pk_add_f32 v[216:217], v[216:217], s[6:7]
	v_pk_add_f32 v[218:219], v[218:219], s[6:7]
	v_pk_add_f32 v[220:221], v[220:221], s[6:7]
	v_rcp_f32_e32 v44, v214
	v_rcp_f32_e32 v45, v215
	v_rcp_f32_e32 v46, v216
	v_rcp_f32_e32 v47, v217
	v_rcp_f32_e32 v48, v218
	v_rcp_f32_e32 v49, v219
	v_rcp_f32_e32 v50, v220
	v_rcp_f32_e32 v51, v221
	v_pk_mul_f32 v[214:215], v[32:33], s[4:5]
	v_pk_mul_f32 v[216:217], v[34:35], s[4:5]
	v_pk_mul_f32 v[218:219], v[36:37], s[4:5]
	v_pk_mul_f32 v[220:221], v[38:39], s[4:5]
	v_exp_f32_e32 v214, v214
	v_exp_f32_e32 v215, v215
	v_exp_f32_e32 v216, v216
	v_exp_f32_e32 v217, v217
	v_exp_f32_e32 v218, v218
	v_exp_f32_e32 v219, v219
	v_exp_f32_e32 v220, v220
	v_exp_f32_e32 v221, v221
	v_pk_add_f32 v[214:215], v[214:215], s[6:7]
	v_pk_add_f32 v[216:217], v[216:217], s[6:7]
	v_pk_add_f32 v[218:219], v[218:219], s[6:7]
	v_pk_add_f32 v[220:221], v[220:221], s[6:7]
	v_rcp_f32_e32 v32, v214
	v_rcp_f32_e32 v33, v215
	v_rcp_f32_e32 v34, v216
	v_rcp_f32_e32 v35, v217
	v_rcp_f32_e32 v36, v218
	v_rcp_f32_e32 v37, v219
	v_rcp_f32_e32 v38, v220
	v_rcp_f32_e32 v39, v221
	v_pk_mul_f32 v[214:215], v[24:25], s[4:5]
	v_pk_mul_f32 v[216:217], v[26:27], s[4:5]
	v_pk_mul_f32 v[218:219], v[28:29], s[4:5]
	v_pk_mul_f32 v[220:221], v[30:31], s[4:5]
	v_exp_f32_e32 v214, v214
	v_exp_f32_e32 v215, v215
	v_exp_f32_e32 v216, v216
	v_exp_f32_e32 v217, v217
	v_exp_f32_e32 v218, v218
	v_exp_f32_e32 v219, v219
	v_exp_f32_e32 v220, v220
	v_exp_f32_e32 v221, v221
	v_pk_add_f32 v[214:215], v[214:215], s[6:7]
	v_pk_add_f32 v[216:217], v[216:217], s[6:7]
	v_pk_add_f32 v[218:219], v[218:219], s[6:7]
	v_pk_add_f32 v[220:221], v[220:221], s[6:7]
	v_rcp_f32_e32 v24, v214
	v_rcp_f32_e32 v25, v215
	v_rcp_f32_e32 v26, v216
	v_rcp_f32_e32 v27, v217
	v_rcp_f32_e32 v28, v218
	v_rcp_f32_e32 v29, v219
	v_rcp_f32_e32 v30, v220
	v_rcp_f32_e32 v31, v221
	v_pk_mul_f32 v[214:215], v[16:17], s[4:5]
	v_pk_mul_f32 v[216:217], v[18:19], s[4:5]
; __device__ __forceinline__ float bf_lo(unsigned w) { return __uint_as_float(w << 16); }
; __device__ __forceinline__ float bf_hi(unsigned w) { return __uint_as_float(w & 0xffff0000u); }
; __device__ __forceinline__ unsigned cvt_pk_bf16(float lo, float hi) { unsigned r; asm volatile("v_cvt_pk_bf16_f32 %0, %1, %2" : "=v"(r) : "v"(lo), "v"(hi)); return r; }
; __device__ __forceinline__ float sigm(float x) { return __builtin_amdgcn_rcpf(1.0f + __expf(-x)); }
; __device__ __forceinline__ float siluf(float x) { return x * __builtin_amdgcn_rcpf(1.0f + __expf(-x)); }
;     __device__ __forceinline__ void operator()(const f32x4 (&acc)[2][2][4][2], const Unit& u, int wr, int wc, int fr, int fq) const {
;     ...
;                 for (int bj = 0; bj < 2; ++bj) { const f32x4 a0 = acc[ai][bj][m][0], a1 = acc[ai][bj][m][1];
;                     float f[8];
; #pragma unroll
;                     for (int q = 0; q < 4; ++q) { f[q] = act_silu ? siluf(a0[q]) : sigm(a0[q]); f[4 + q] = act_silu ? siluf(a1[q]) : sigm(a1[q]); }
;                     if (ldp) { const u32x4 o = old8[m][bj];
;                         if (recip) { f[0] *= __builtin_amdgcn_rcpf(bf_lo(o.x)); f[1] *= __builtin_amdgcn_rcpf(bf_hi(o.x)); f[2] *= __builtin_amdgcn_rcpf(bf_lo(o.y)); f[3] *= __builtin_amdgcn_rcpf(bf_hi(o.y));
;                             f[4] *= __builtin_amdgcn_rcpf(bf_lo(o.z)); f[5] *= __builtin_amdgcn_rcpf(bf_hi(o.z)); f[6] *= __builtin_amdgcn_rcpf(bf_lo(o.w)); f[7] *= __builtin_amdgcn_rcpf(bf_hi(o.w)); }
;                         else { f[0] *= bf_lo(o.x); f[1] *= bf_hi(o.x); f[2] *= bf_lo(o.y); f[3] *= bf_hi(o.y); f[4] *= bf_lo(o.z); f[5] *= bf_hi(o.z); f[6] *= bf_lo(o.w); f[7] *= bf_hi(o.w); } }
;                     u32x4 w; w.x = cvt_pk_bf16(f[0], f[1]); w.y = cvt_pk_bf16(f[2], f[3]); w.z = cvt_pk_bf16(f[4], f[5]); w.w = cvt_pk_bf16(f[6], f[7]);
;                     if (st_lm) { if (recip) __builtin_nontemporal_store(w, (u32x4*)(stp + ((ai * 4 + m) * 2 + bj) * 512)); else *(u32x4*)(stp + ((ai * 4 + m) * 2 + bj) * 512) = w; }
;                     else *(u32x4*)(stp + (size_t)(row0 + ai * 128 + m * 16) * ld + col0 + bj * 128) = w; } }
	v_pk_mul_f32 v[218:219], v[20:21], s[4:5]
	v_pk_mul_f32 v[220:221], v[22:23], s[4:5]
	v_exp_f32_e32 v214, v214
	v_exp_f32_e32 v215, v215
	v_exp_f32_e32 v216, v216
	v_exp_f32_e32 v217, v217
	v_exp_f32_e32 v218, v218
	v_exp_f32_e32 v219, v219
	v_exp_f32_e32 v220, v220
	v_exp_f32_e32 v221, v221
	v_pk_add_f32 v[214:215], v[214:215], s[6:7]
	v_pk_add_f32 v[216:217], v[216:217], s[6:7]
	v_pk_add_f32 v[218:219], v[218:219], s[6:7]
	v_pk_add_f32 v[220:221], v[220:221], s[6:7]
	v_rcp_f32_e32 v16, v214
	v_rcp_f32_e32 v17, v215
	v_rcp_f32_e32 v18, v216
	v_rcp_f32_e32 v19, v217
	v_rcp_f32_e32 v20, v218
	v_rcp_f32_e32 v21, v219
	v_rcp_f32_e32 v22, v220
	v_rcp_f32_e32 v23, v221
	v_pk_mul_f32 v[214:215], v[8:9], s[4:5]
	v_pk_mul_f32 v[216:217], v[10:11], s[4:5]
	v_pk_mul_f32 v[218:219], v[12:13], s[4:5]
	v_pk_mul_f32 v[220:221], v[14:15], s[4:5]
	v_exp_f32_e32 v214, v214
	v_exp_f32_e32 v215, v215
	v_exp_f32_e32 v216, v216
	v_exp_f32_e32 v217, v217
	v_exp_f32_e32 v218, v218
	v_exp_f32_e32 v219, v219
	v_exp_f32_e32 v220, v220
	v_exp_f32_e32 v221, v221
	v_pk_add_f32 v[214:215], v[214:215], s[6:7]
	v_pk_add_f32 v[216:217], v[216:217], s[6:7]
	v_pk_add_f32 v[218:219], v[218:219], s[6:7]
	v_pk_add_f32 v[220:221], v[220:221], s[6:7]
	v_rcp_f32_e32 v8, v214
	v_rcp_f32_e32 v9, v215
	v_rcp_f32_e32 v10, v216
	v_rcp_f32_e32 v11, v217
	v_rcp_f32_e32 v12, v218
	v_rcp_f32_e32 v13, v219
	v_rcp_f32_e32 v14, v220
	v_rcp_f32_e32 v15, v221
	v_pk_mul_f32 v[214:215], v[0:1], s[4:5]
	v_pk_mul_f32 v[216:217], v[2:3], s[4:5]
	v_pk_mul_f32 v[218:219], v[4:5], s[4:5]
	v_pk_mul_f32 v[220:221], v[6:7], s[4:5]
	v_exp_f32_e32 v214, v214
	v_exp_f32_e32 v215, v215
	v_exp_f32_e32 v216, v216
	v_exp_f32_e32 v217, v217
	v_exp_f32_e32 v218, v218
	v_exp_f32_e32 v219, v219
	v_exp_f32_e32 v220, v220
	v_exp_f32_e32 v221, v221
	v_pk_add_f32 v[214:215], v[214:215], s[6:7]
	v_pk_add_f32 v[216:217], v[216:217], s[6:7]
	v_pk_add_f32 v[218:219], v[218:219], s[6:7]
	v_pk_add_f32 v[220:221], v[220:221], s[6:7]
	v_rcp_f32_e32 v0, v214
	v_rcp_f32_e32 v1, v215
	v_rcp_f32_e32 v2, v216
	v_rcp_f32_e32 v3, v217
	v_rcp_f32_e32 v4, v218
	v_rcp_f32_e32 v5, v219
	v_rcp_f32_e32 v6, v220
	v_rcp_f32_e32 v7, v221
	s_waitcnt vmcnt(15)
	v_lshlrev_b32_e32 v214, 16, v116
	v_and_b32_e32 v215, s1, v116
	v_lshlrev_b32_e32 v216, 16, v117
	v_and_b32_e32 v217, s1, v117
	v_lshlrev_b32_e32 v218, 16, v118
	v_and_b32_e32 v219, s1, v118
	v_lshlrev_b32_e32 v220, 16, v119
	v_and_b32_e32 v221, s1, v119
	v_pk_mul_f32 v[156:157], v[156:157], v[214:215]
	v_pk_mul_f32 v[158:159], v[158:159], v[216:217]
	v_pk_mul_f32 v[152:153], v[152:153], v[218:219]
	v_pk_mul_f32 v[154:155], v[154:155], v[220:221]
	v_cvt_pk_bf16_f32 v116, v156, v157
	v_cvt_pk_bf16_f32 v117, v158, v159
	v_cvt_pk_bf16_f32 v118, v152, v153
	v_cvt_pk_bf16_f32 v119, v154, v155
	global_store_dwordx4 v[196:197], v[116:119], off
	s_waitcnt vmcnt(15)
	v_lshlrev_b32_e32 v214, 16, v104
	v_and_b32_e32 v215, s1, v104
	v_lshlrev_b32_e32 v216, 16, v105
	v_and_b32_e32 v217, s1, v105
	v_lshlrev_b32_e32 v218, 16, v106
	v_and_b32_e32 v219, s1, v106
	v_lshlrev_b32_e32 v220, 16, v107
	v_and_b32_e32 v221, s1, v107
	v_pk_mul_f32 v[148:149], v[148:149], v[214:215]
	v_pk_mul_f32 v[150:151], v[150:151], v[216:217]
	v_pk_mul_f32 v[144:145], v[144:145], v[218:219]
	v_pk_mul_f32 v[146:147], v[146:147], v[220:221]
	v_cvt_pk_bf16_f32 v104, v148, v149
	v_cvt_pk_bf16_f32 v105, v150, v151
	v_cvt_pk_bf16_f32 v106, v144, v145
	v_cvt_pk_bf16_f32 v107, v146, v147
	global_store_dwordx4 v[196:197], v[104:107], off offset:1024
	s_waitcnt vmcnt(15)
	v_lshlrev_b32_e32 v214, 16, v92
	v_and_b32_e32 v215, s1, v92
	v_lshlrev_b32_e32 v216, 16, v93
	v_and_b32_e32 v217, s1, v93
	v_lshlrev_b32_e32 v218, 16, v94
	v_and_b32_e32 v219, s1, v94
	v_lshlrev_b32_e32 v220, 16, v95
	v_and_b32_e32 v221, s1, v95
	v_pk_mul_f32 v[140:141], v[140:141], v[214:215]
	v_pk_mul_f32 v[142:143], v[142:143], v[216:217]
	v_pk_mul_f32 v[136:137], v[136:137], v[218:219]
	v_pk_mul_f32 v[138:139], v[138:139], v[220:221]
	v_cvt_pk_bf16_f32 v92, v140, v141
	v_cvt_pk_bf16_f32 v93, v142, v143
	v_cvt_pk_bf16_f32 v94, v136, v137
	v_cvt_pk_bf16_f32 v95, v138, v139
	global_store_dwordx4 v[196:197], v[92:95], off offset:2048
	s_waitcnt vmcnt(15)
	v_lshlrev_b32_e32 v214, 16, v80
	v_and_b32_e32 v215, s1, v80
	v_lshlrev_b32_e32 v216, 16, v81
	v_and_b32_e32 v217, s1, v81
	v_lshlrev_b32_e32 v218, 16, v82
	v_and_b32_e32 v219, s1, v82
	v_lshlrev_b32_e32 v220, 16, v83
	v_and_b32_e32 v221, s1, v83
	v_pk_mul_f32 v[132:133], v[132:133], v[214:215]
	v_pk_mul_f32 v[134:135], v[134:135], v[216:217]
	v_pk_mul_f32 v[128:129], v[128:129], v[218:219]
	v_pk_mul_f32 v[130:131], v[130:131], v[220:221]
	v_cvt_pk_bf16_f32 v80, v132, v133
	v_cvt_pk_bf16_f32 v81, v134, v135
	v_cvt_pk_bf16_f32 v82, v128, v129
	v_cvt_pk_bf16_f32 v83, v130, v131
	global_store_dwordx4 v[196:197], v[80:83], off offset:3072
	s_waitcnt vmcnt(15)
	v_lshlrev_b32_e32 v214, 16, v76
	v_and_b32_e32 v215, s1, v76
	v_lshlrev_b32_e32 v216, 16, v77
	v_and_b32_e32 v217, s1, v77
	v_lshlrev_b32_e32 v218, 16, v78
	v_and_b32_e32 v219, s1, v78
	v_lshlrev_b32_e32 v220, 16, v79
	v_and_b32_e32 v221, s1, v79
	v_pk_mul_f32 v[124:125], v[124:125], v[214:215]
	v_pk_mul_f32 v[126:127], v[126:127], v[216:217]
	v_pk_mul_f32 v[120:121], v[120:121], v[218:219]
	v_pk_mul_f32 v[122:123], v[122:123], v[220:221]
	v_cvt_pk_bf16_f32 v76, v124, v125
	v_cvt_pk_bf16_f32 v77, v126, v127
	v_cvt_pk_bf16_f32 v78, v120, v121
	v_cvt_pk_bf16_f32 v79, v122, v123
	global_store_dwordx4 v[198:199], v[76:79], off
	s_waitcnt vmcnt(15)
; __device__ __forceinline__ float bf_lo(unsigned w) { return __uint_as_float(w << 16); }
; __device__ __forceinline__ float bf_hi(unsigned w) { return __uint_as_float(w & 0xffff0000u); }
; __device__ __forceinline__ unsigned cvt_pk_bf16(float lo, float hi) { unsigned r; asm volatile("v_cvt_pk_bf16_f32 %0, %1, %2" : "=v"(r) : "v"(lo), "v"(hi)); return r; }
;     __device__ __forceinline__ void operator()(const f32x4 (&acc)[2][2][4][2], const Unit& u, int wr, int wc, int fr, int fq) const {
;     ...
;                     if (ldp) { const u32x4 o = old8[m][bj];
;                         if (recip) { f[0] *= __builtin_amdgcn_rcpf(bf_lo(o.x)); f[1] *= __builtin_amdgcn_rcpf(bf_hi(o.x)); f[2] *= __builtin_amdgcn_rcpf(bf_lo(o.y)); f[3] *= __builtin_amdgcn_rcpf(bf_hi(o.y));
;                             f[4] *= __builtin_amdgcn_rcpf(bf_lo(o.z)); f[5] *= __builtin_amdgcn_rcpf(bf_hi(o.z)); f[6] *= __builtin_amdgcn_rcpf(bf_lo(o.w)); f[7] *= __builtin_amdgcn_rcpf(bf_hi(o.w)); }
;                         else { f[0] *= bf_lo(o.x); f[1] *= bf_hi(o.x); f[2] *= bf_lo(o.y); f[3] *= bf_hi(o.y); f[4] *= bf_lo(o.z); f[5] *= bf_hi(o.z); f[6] *= bf_lo(o.w); f[7] *= bf_hi(o.w); } }
;                     u32x4 w; w.x = cvt_pk_bf16(f[0], f[1]); w.y = cvt_pk_bf16(f[2], f[3]); w.z = cvt_pk_bf16(f[4], f[5]); w.w = cvt_pk_bf16(f[6], f[7]);
;                     if (st_lm) { if (recip) __builtin_nontemporal_store(w, (u32x4*)(stp + ((ai * 4 + m) * 2 + bj) * 512)); else *(u32x4*)(stp + ((ai * 4 + m) * 2 + bj) * 512) = w; }
;                     else *(u32x4*)(stp + (size_t)(row0 + ai * 128 + m * 16) * ld + col0 + bj * 128) = w; } }
	v_lshlrev_b32_e32 v214, 16, v64
	v_and_b32_e32 v215, s1, v64
	v_lshlrev_b32_e32 v216, 16, v65
	v_and_b32_e32 v217, s1, v65
	v_lshlrev_b32_e32 v218, 16, v66
	v_and_b32_e32 v219, s1, v66
	v_lshlrev_b32_e32 v220, 16, v67
	v_and_b32_e32 v221, s1, v67
	v_pk_mul_f32 v[112:113], v[112:113], v[214:215]
	v_pk_mul_f32 v[114:115], v[114:115], v[216:217]
	v_pk_mul_f32 v[108:109], v[108:109], v[218:219]
	v_pk_mul_f32 v[110:111], v[110:111], v[220:221]
	v_cvt_pk_bf16_f32 v64, v112, v113
	v_cvt_pk_bf16_f32 v65, v114, v115
	v_cvt_pk_bf16_f32 v66, v108, v109
	v_cvt_pk_bf16_f32 v67, v110, v111
	global_store_dwordx4 v[198:199], v[64:67], off offset:1024
	s_waitcnt vmcnt(15)
	v_lshlrev_b32_e32 v214, 16, v52
	v_and_b32_e32 v215, s1, v52
	v_lshlrev_b32_e32 v216, 16, v53
	v_and_b32_e32 v217, s1, v53
	v_lshlrev_b32_e32 v218, 16, v54
	v_and_b32_e32 v219, s1, v54
	v_lshlrev_b32_e32 v220, 16, v55
	v_and_b32_e32 v221, s1, v55
	v_pk_mul_f32 v[100:101], v[100:101], v[214:215]
	v_pk_mul_f32 v[102:103], v[102:103], v[216:217]
	v_pk_mul_f32 v[96:97], v[96:97], v[218:219]
	v_pk_mul_f32 v[98:99], v[98:99], v[220:221]
	v_cvt_pk_bf16_f32 v52, v100, v101
	v_cvt_pk_bf16_f32 v53, v102, v103
	v_cvt_pk_bf16_f32 v54, v96, v97
	v_cvt_pk_bf16_f32 v55, v98, v99
	global_store_dwordx4 v[198:199], v[52:55], off offset:2048
	s_waitcnt vmcnt(15)
	v_lshlrev_b32_e32 v214, 16, v40
	v_and_b32_e32 v215, s1, v40
	v_lshlrev_b32_e32 v216, 16, v41
	v_and_b32_e32 v217, s1, v41
	v_lshlrev_b32_e32 v218, 16, v42
	v_and_b32_e32 v219, s1, v42
	v_lshlrev_b32_e32 v220, 16, v43
	v_and_b32_e32 v221, s1, v43
	v_pk_mul_f32 v[88:89], v[88:89], v[214:215]
	v_pk_mul_f32 v[90:91], v[90:91], v[216:217]
	v_pk_mul_f32 v[84:85], v[84:85], v[218:219]
	v_pk_mul_f32 v[86:87], v[86:87], v[220:221]
	v_cvt_pk_bf16_f32 v40, v88, v89
	v_cvt_pk_bf16_f32 v41, v90, v91
	v_cvt_pk_bf16_f32 v42, v84, v85
	v_cvt_pk_bf16_f32 v43, v86, v87
	global_store_dwordx4 v[198:199], v[40:43], off offset:3072
	s_waitcnt vmcnt(15)
	v_lshlrev_b32_e32 v214, 16, v228
	v_and_b32_e32 v215, s1, v228
	v_lshlrev_b32_e32 v216, 16, v229
	v_and_b32_e32 v217, s1, v229
	v_lshlrev_b32_e32 v218, 16, v230
	v_and_b32_e32 v219, s1, v230
	v_lshlrev_b32_e32 v220, 16, v231
	v_and_b32_e32 v221, s1, v231
	v_pk_mul_f32 v[72:73], v[72:73], v[214:215]
	v_pk_mul_f32 v[74:75], v[74:75], v[216:217]
	v_pk_mul_f32 v[68:69], v[68:69], v[218:219]
	v_pk_mul_f32 v[70:71], v[70:71], v[220:221]
	v_cvt_pk_bf16_f32 v228, v72, v73
	v_cvt_pk_bf16_f32 v229, v74, v75
	v_cvt_pk_bf16_f32 v230, v68, v69
	v_cvt_pk_bf16_f32 v231, v70, v71
	global_store_dwordx4 v[200:201], v[228:231], off
	s_waitcnt vmcnt(15)
	v_lshlrev_b32_e32 v214, 16, v232
	v_and_b32_e32 v215, s1, v232
	v_lshlrev_b32_e32 v216, 16, v233
	v_and_b32_e32 v217, s1, v233
	v_lshlrev_b32_e32 v218, 16, v234
	v_and_b32_e32 v219, s1, v234
	v_lshlrev_b32_e32 v220, 16, v235
	v_and_b32_e32 v221, s1, v235
	v_pk_mul_f32 v[60:61], v[60:61], v[214:215]
	v_pk_mul_f32 v[62:63], v[62:63], v[216:217]
	v_pk_mul_f32 v[56:57], v[56:57], v[218:219]
	v_pk_mul_f32 v[58:59], v[58:59], v[220:221]
	v_cvt_pk_bf16_f32 v232, v60, v61
	v_cvt_pk_bf16_f32 v233, v62, v63
	v_cvt_pk_bf16_f32 v234, v56, v57
	v_cvt_pk_bf16_f32 v235, v58, v59
	global_store_dwordx4 v[200:201], v[232:235], off offset:1024
	s_waitcnt vmcnt(15)
; __device__ __forceinline__ float bf_lo(unsigned w) { return __uint_as_float(w << 16); }
; __device__ __forceinline__ float bf_hi(unsigned w) { return __uint_as_float(w & 0xffff0000u); }
; __device__ __forceinline__ unsigned cvt_pk_bf16(float lo, float hi) { unsigned r; asm volatile("v_cvt_pk_bf16_f32 %0, %1, %2" : "=v"(r) : "v"(lo), "v"(hi)); return r; }
;     __device__ __forceinline__ void operator()(const f32x4 (&acc)[2][2][4][2], const Unit& u, int wr, int wc, int fr, int fq) const {
;     ...
;                     if (ldp) { const u32x4 o = old8[m][bj];
;                         if (recip) { f[0] *= __builtin_amdgcn_rcpf(bf_lo(o.x)); f[1] *= __builtin_amdgcn_rcpf(bf_hi(o.x)); f[2] *= __builtin_amdgcn_rcpf(bf_lo(o.y)); f[3] *= __builtin_amdgcn_rcpf(bf_hi(o.y));
;                             f[4] *= __builtin_amdgcn_rcpf(bf_lo(o.z)); f[5] *= __builtin_amdgcn_rcpf(bf_hi(o.z)); f[6] *= __builtin_amdgcn_rcpf(bf_lo(o.w)); f[7] *= __builtin_amdgcn_rcpf(bf_hi(o.w)); }
;                         else { f[0] *= bf_lo(o.x); f[1] *= bf_hi(o.x); f[2] *= bf_lo(o.y); f[3] *= bf_hi(o.y); f[4] *= bf_lo(o.z); f[5] *= bf_hi(o.z); f[6] *= bf_lo(o.w); f[7] *= bf_hi(o.w); } }
;                     u32x4 w; w.x = cvt_pk_bf16(f[0], f[1]); w.y = cvt_pk_bf16(f[2], f[3]); w.z = cvt_pk_bf16(f[4], f[5]); w.w = cvt_pk_bf16(f[6], f[7]);
;                     if (st_lm) { if (recip) __builtin_nontemporal_store(w, (u32x4*)(stp + ((ai * 4 + m) * 2 + bj) * 512)); else *(u32x4*)(stp + ((ai * 4 + m) * 2 + bj) * 512) = w; }
;                     else *(u32x4*)(stp + (size_t)(row0 + ai * 128 + m * 16) * ld + col0 + bj * 128) = w; } }
	v_lshlrev_b32_e32 v214, 16, v236
	v_and_b32_e32 v215, s1, v236
	v_lshlrev_b32_e32 v216, 16, v237
	v_and_b32_e32 v217, s1, v237
	v_lshlrev_b32_e32 v218, 16, v238
	v_and_b32_e32 v219, s1, v238
	v_lshlrev_b32_e32 v220, 16, v239
	v_and_b32_e32 v221, s1, v239
	v_pk_mul_f32 v[48:49], v[48:49], v[214:215]
	v_pk_mul_f32 v[50:51], v[50:51], v[216:217]
	v_pk_mul_f32 v[44:45], v[44:45], v[218:219]
	v_pk_mul_f32 v[46:47], v[46:47], v[220:221]
	v_cvt_pk_bf16_f32 v236, v48, v49
	v_cvt_pk_bf16_f32 v237, v50, v51
	v_cvt_pk_bf16_f32 v238, v44, v45
	v_cvt_pk_bf16_f32 v239, v46, v47
	global_store_dwordx4 v[200:201], v[236:239], off offset:2048
	s_waitcnt vmcnt(15)
	v_lshlrev_b32_e32 v214, 16, v240
	v_and_b32_e32 v215, s1, v240
	v_lshlrev_b32_e32 v216, 16, v241
	v_and_b32_e32 v217, s1, v241
	v_lshlrev_b32_e32 v218, 16, v242
	v_and_b32_e32 v219, s1, v242
	v_lshlrev_b32_e32 v220, 16, v243
	v_and_b32_e32 v221, s1, v243
	v_pk_mul_f32 v[36:37], v[36:37], v[214:215]
	v_pk_mul_f32 v[38:39], v[38:39], v[216:217]
	v_pk_mul_f32 v[32:33], v[32:33], v[218:219]
	v_pk_mul_f32 v[34:35], v[34:35], v[220:221]
	v_cvt_pk_bf16_f32 v240, v36, v37
	v_cvt_pk_bf16_f32 v241, v38, v39
	v_cvt_pk_bf16_f32 v242, v32, v33
	v_cvt_pk_bf16_f32 v243, v34, v35
	global_store_dwordx4 v[200:201], v[240:243], off offset:3072
	s_waitcnt vmcnt(15)
	v_lshlrev_b32_e32 v214, 16, v244
	v_and_b32_e32 v215, s1, v244
	v_lshlrev_b32_e32 v216, 16, v245
	v_and_b32_e32 v217, s1, v245
	v_lshlrev_b32_e32 v218, 16, v246
	v_and_b32_e32 v219, s1, v246
	v_lshlrev_b32_e32 v220, 16, v247
	v_and_b32_e32 v221, s1, v247
	v_pk_mul_f32 v[28:29], v[28:29], v[214:215]
	v_pk_mul_f32 v[30:31], v[30:31], v[216:217]
	v_pk_mul_f32 v[24:25], v[24:25], v[218:219]
	v_pk_mul_f32 v[26:27], v[26:27], v[220:221]
	v_cvt_pk_bf16_f32 v244, v28, v29
	v_cvt_pk_bf16_f32 v245, v30, v31
	v_cvt_pk_bf16_f32 v246, v24, v25
	v_cvt_pk_bf16_f32 v247, v26, v27
	global_store_dwordx4 v[202:203], v[244:247], off
	s_waitcnt vmcnt(15)
	v_lshlrev_b32_e32 v214, 16, v248
	v_and_b32_e32 v215, s1, v248
	v_lshlrev_b32_e32 v216, 16, v249
	v_and_b32_e32 v217, s1, v249
	v_lshlrev_b32_e32 v218, 16, v250
	v_and_b32_e32 v219, s1, v250
	v_lshlrev_b32_e32 v220, 16, v251
	v_and_b32_e32 v221, s1, v251
	v_pk_mul_f32 v[20:21], v[20:21], v[214:215]
	v_pk_mul_f32 v[22:23], v[22:23], v[216:217]
	v_pk_mul_f32 v[16:17], v[16:17], v[218:219]
	v_pk_mul_f32 v[18:19], v[18:19], v[220:221]
	v_cvt_pk_bf16_f32 v248, v20, v21
	v_cvt_pk_bf16_f32 v249, v22, v23
	v_cvt_pk_bf16_f32 v250, v16, v17
	v_cvt_pk_bf16_f32 v251, v18, v19
	global_store_dwordx4 v[202:203], v[248:251], off offset:1024
	s_waitcnt vmcnt(15)
	v_lshlrev_b32_e32 v214, 16, v206
	v_and_b32_e32 v215, s1, v206
	v_lshlrev_b32_e32 v216, 16, v207
	v_and_b32_e32 v217, s1, v207
	v_lshlrev_b32_e32 v218, 16, v208
	v_and_b32_e32 v219, s1, v208
	v_lshlrev_b32_e32 v220, 16, v209
	v_and_b32_e32 v221, s1, v209
	v_pk_mul_f32 v[12:13], v[12:13], v[214:215]
	v_pk_mul_f32 v[14:15], v[14:15], v[216:217]
	v_pk_mul_f32 v[8:9], v[8:9], v[218:219]
	v_pk_mul_f32 v[10:11], v[10:11], v[220:221]
	v_cvt_pk_bf16_f32 v206, v12, v13
	v_cvt_pk_bf16_f32 v207, v14, v15
	v_cvt_pk_bf16_f32 v208, v8, v9
	v_cvt_pk_bf16_f32 v209, v10, v11
	global_store_dwordx4 v[202:203], v[206:209], off offset:2048
	s_waitcnt vmcnt(15)
	v_lshlrev_b32_e32 v214, 16, v210
	v_and_b32_e32 v215, s1, v210
	v_lshlrev_b32_e32 v216, 16, v211
	v_and_b32_e32 v217, s1, v211
	v_lshlrev_b32_e32 v218, 16, v212
	v_and_b32_e32 v219, s1, v212
	v_lshlrev_b32_e32 v220, 16, v213
	v_and_b32_e32 v221, s1, v213
	v_pk_mul_f32 v[4:5], v[4:5], v[214:215]
	v_pk_mul_f32 v[6:7], v[6:7], v[216:217]
	v_pk_mul_f32 v[0:1], v[0:1], v[218:219]
	v_pk_mul_f32 v[2:3], v[2:3], v[220:221]
	v_cvt_pk_bf16_f32 v210, v4, v5
	v_cvt_pk_bf16_f32 v211, v6, v7
	v_cvt_pk_bf16_f32 v212, v0, v1
	v_cvt_pk_bf16_f32 v213, v2, v3
	global_store_dwordx4 v[202:203], v[210:213], off offset:3072
	s_branch .LBB0_727
